# v12: write-through (sc1) stores in the G1/G3/G5 GEMM epilogues so the barrier release has less to write back; on top of v11
# speedup vs baseline: 1.0479x; 1.0040x over previous
; DI unsigned cvt_pk(float lo, float hi) { unsigned r; asm("v_cvt_pk_bf16_f32 %0, %1, %2" : "=v"(r) : "v"(lo), "v"(hi)); return r; }
; DI float siluf_(float x) { return x * sigmoidf_(x); }
;     __device__ __forceinline__ void operator()(const f32x4 (&acc)[2][2][4][2], const Unit& u, int wr, int wc, int fr, int fq) const {
;         const int row0 = u.pm * BM + wr * 64 + fr, col0 = u.pn * 128 + wc * 32 + 8 * fq;
; #pragma unroll
;         for (int ai = 0; ai < 2; ++ai)
; #pragma unroll
;             for (int m = 0; m < 4; ++m) {
;                 const int row = row0 + ai * HALF + m * 16;
;                 const float rs = rsqrtf(ss[row] * (1.f / DM) + EPS);
;                 float h[8];
; #pragma unroll
;                 for (int n = 0; n < 2; ++n)
; #pragma unroll
;                     for (int j = 0; j < 4; ++j) { const float gg = acc[ai][0][m][n][j] * rs, uu = acc[ai][1][m][n][j] * rs; h[4 * n + j] = siluf_(gg) * uu; }
;                 u32x4 w; w.x = cvt_pk(h[0], h[1]); w.y = cvt_pk(h[2], h[3]); w.z = cvt_pk(h[4], h[5]); w.w = cvt_pk(h[6], h[7]);
;                 *(u32x4*)(H + (size_t)row * DFF + col0) = w;
.LBB0_297:
	v_lshl_add_u32 v138, s41, 8, v155
	v_ashrrev_i32_e32 v139, 31, v138
	v_lshl_add_u64 v[140:141], v[138:139], 2, s[10:11]
	global_load_dword v139, v[140:141], off
	global_load_dword v162, v[140:141], off offset:64
	global_load_dword v163, v[140:141], off offset:128
	global_load_dword v164, v[140:141], off offset:192
	global_load_dword v165, v[140:141], off offset:512
	global_load_dword v166, v[140:141], off offset:576
	global_load_dword v167, v[140:141], off offset:640
	global_load_dword v168, v[140:141], off offset:704
	s_mov_b32 s15, 0x800000
	v_lshl_or_b32 v142, s40, 7, v157
	v_ashrrev_i32_e32 v143, 31, v142
	v_mov_b64_e32 v[186:187], s[8:9]
	v_lshlrev_b64 v[188:189], 1, v[142:143]
	s_waitcnt vmcnt(0)
	v_fmamk_f32 v180, v139, 0x3a800000, v217
	v_cmp_gt_f32_e32 vcc, s15, v180
	v_mul_f32_e32 v181, 0x4b800000, v180
	s_nop 0
	v_cndmask_b32_e32 v180, v180, v181, vcc
	v_rsq_f32_e32 v180, v180
	v_add_u32_e32 v182, 0, v138
	v_mul_f32_e32 v181, 0x45800000, v180
	v_cndmask_b32_e32 v180, v180, v181, vcc
	v_mul_f32_e32 v124, v124, v180
	v_mul_f32_e32 v120, v120, v180
	v_mul_f32_e32 v125, v125, v180
	v_mul_f32_e32 v121, v121, v180
	v_mul_f32_e32 v126, v126, v180
	v_mul_f32_e32 v122, v122, v180
	v_mul_f32_e32 v127, v127, v180
	v_mul_f32_e32 v123, v123, v180
	v_mul_f32_e32 v116, v116, v180
	v_mul_f32_e32 v112, v112, v180
	v_mul_f32_e32 v117, v117, v180
	v_mul_f32_e32 v113, v113, v180
	v_mul_f32_e32 v118, v118, v180
	v_mul_f32_e32 v114, v114, v180
	v_mul_f32_e32 v119, v119, v180
	v_mul_f32_e32 v115, v115, v180
	v_mul_f32_e32 v172, 0xbfb8aa3b, v124
	v_mul_f32_e32 v173, 0xbfb8aa3b, v125
	v_mul_f32_e32 v174, 0xbfb8aa3b, v126
	v_mul_f32_e32 v175, 0xbfb8aa3b, v127
	v_mul_f32_e32 v176, 0xbfb8aa3b, v116
	v_mul_f32_e32 v177, 0xbfb8aa3b, v117
	v_mul_f32_e32 v178, 0xbfb8aa3b, v118
	v_mul_f32_e32 v179, 0xbfb8aa3b, v119
	v_exp_f32_e32 v172, v172
	v_exp_f32_e32 v173, v173
	v_exp_f32_e32 v174, v174
	v_exp_f32_e32 v175, v175
	v_exp_f32_e32 v176, v176
	v_exp_f32_e32 v177, v177
	v_exp_f32_e32 v178, v178
	v_exp_f32_e32 v179, v179
	v_add_f32_e32 v172, 1.0, v172
	v_add_f32_e32 v173, 1.0, v173
	v_add_f32_e32 v174, 1.0, v174
	v_add_f32_e32 v175, 1.0, v175
	v_add_f32_e32 v176, 1.0, v176
	v_add_f32_e32 v177, 1.0, v177
	v_add_f32_e32 v178, 1.0, v178
	v_add_f32_e32 v179, 1.0, v179
	v_rcp_f32_e32 v172, v172
	v_rcp_f32_e32 v173, v173
	v_rcp_f32_e32 v174, v174
	v_rcp_f32_e32 v175, v175
	v_rcp_f32_e32 v176, v176
	v_rcp_f32_e32 v177, v177
	v_rcp_f32_e32 v178, v178
	v_rcp_f32_e32 v179, v179
	v_mul_f32_e32 v124, v124, v172
	v_mul_f32_e32 v125, v125, v173
	v_mul_f32_e32 v126, v126, v174
	v_mul_f32_e32 v127, v127, v175
	v_mul_f32_e32 v116, v116, v176
	v_mul_f32_e32 v117, v117, v177
	v_mul_f32_e32 v118, v118, v178
	v_mul_f32_e32 v119, v119, v179
	v_mul_f32_e32 v124, v120, v124
	v_mul_f32_e32 v125, v121, v125
	v_mul_f32_e32 v126, v122, v126
	v_mul_f32_e32 v127, v123, v127
	v_mul_f32_e32 v116, v112, v116
	v_mul_f32_e32 v117, v113, v117
	v_mul_f32_e32 v118, v114, v118
	v_mul_f32_e32 v119, v115, v119
	v_mad_i64_i32 v[184:185], s[2:3], v182, s64, v[186:187]
	v_cvt_pk_bf16_f32 v172, v124, v125
	v_cvt_pk_bf16_f32 v173, v126, v127
	v_cvt_pk_bf16_f32 v174, v116, v117
	v_cvt_pk_bf16_f32 v175, v118, v119
	v_lshl_add_u64 v[184:185], v[184:185], 0, v[188:189]
	global_store_dwordx4 v[184:185], v[172:175], off sc1
	v_fmamk_f32 v180, v162, 0x3a800000, v217
	v_cmp_gt_f32_e32 vcc, s15, v180
	v_mul_f32_e32 v181, 0x4b800000, v180
	s_nop 0
	v_cndmask_b32_e32 v180, v180, v181, vcc
	v_rsq_f32_e32 v180, v180
	v_add_u32_e32 v182, 16, v138
	v_mul_f32_e32 v181, 0x45800000, v180
	v_cndmask_b32_e32 v180, v180, v181, vcc
	v_mul_f32_e32 v108, v108, v180
	v_mul_f32_e32 v104, v104, v180
	v_mul_f32_e32 v109, v109, v180
	v_mul_f32_e32 v105, v105, v180
	v_mul_f32_e32 v110, v110, v180
	v_mul_f32_e32 v106, v106, v180
	v_mul_f32_e32 v111, v111, v180
	v_mul_f32_e32 v107, v107, v180
	v_mul_f32_e32 v100, v100, v180
	v_mul_f32_e32 v96, v96, v180
	v_mul_f32_e32 v101, v101, v180
	v_mul_f32_e32 v97, v97, v180
	v_mul_f32_e32 v102, v102, v180
	v_mul_f32_e32 v98, v98, v180
	v_mul_f32_e32 v103, v103, v180
	v_mul_f32_e32 v99, v99, v180
	v_mul_f32_e32 v172, 0xbfb8aa3b, v108
	v_mul_f32_e32 v173, 0xbfb8aa3b, v109
	v_mul_f32_e32 v174, 0xbfb8aa3b, v110
	v_mul_f32_e32 v175, 0xbfb8aa3b, v111
	v_mul_f32_e32 v176, 0xbfb8aa3b, v100
	v_mul_f32_e32 v177, 0xbfb8aa3b, v101
	v_mul_f32_e32 v178, 0xbfb8aa3b, v102
	v_mul_f32_e32 v179, 0xbfb8aa3b, v103
	v_exp_f32_e32 v172, v172
	v_exp_f32_e32 v173, v173
	v_exp_f32_e32 v174, v174
	v_exp_f32_e32 v175, v175
	v_exp_f32_e32 v176, v176
	v_exp_f32_e32 v177, v177
	v_exp_f32_e32 v178, v178
	v_exp_f32_e32 v179, v179
	v_add_f32_e32 v172, 1.0, v172
	v_add_f32_e32 v173, 1.0, v173
	v_add_f32_e32 v174, 1.0, v174
	v_add_f32_e32 v175, 1.0, v175
	v_add_f32_e32 v176, 1.0, v176
	v_add_f32_e32 v177, 1.0, v177
	v_add_f32_e32 v178, 1.0, v178
	v_add_f32_e32 v179, 1.0, v179
	v_rcp_f32_e32 v172, v172
	v_rcp_f32_e32 v173, v173
	v_rcp_f32_e32 v174, v174
	v_rcp_f32_e32 v175, v175
	v_rcp_f32_e32 v176, v176
	v_rcp_f32_e32 v177, v177
	v_rcp_f32_e32 v178, v178
	v_rcp_f32_e32 v179, v179
	v_mul_f32_e32 v108, v108, v172
	v_mul_f32_e32 v109, v109, v173
	v_mul_f32_e32 v110, v110, v174
	v_mul_f32_e32 v111, v111, v175
	v_mul_f32_e32 v100, v100, v176
	v_mul_f32_e32 v101, v101, v177
	v_mul_f32_e32 v102, v102, v178
	v_mul_f32_e32 v103, v103, v179
	v_mul_f32_e32 v108, v104, v108
	v_mul_f32_e32 v109, v105, v109
	v_mul_f32_e32 v110, v106, v110
	v_mul_f32_e32 v111, v107, v111
	v_mul_f32_e32 v100, v96, v100
	v_mul_f32_e32 v101, v97, v101
	v_mul_f32_e32 v102, v98, v102
	v_mul_f32_e32 v103, v99, v103
	v_mad_i64_i32 v[184:185], s[2:3], v182, s64, v[186:187]
; DI unsigned cvt_pk(float lo, float hi) { unsigned r; asm("v_cvt_pk_bf16_f32 %0, %1, %2" : "=v"(r) : "v"(lo), "v"(hi)); return r; }
; DI float siluf_(float x) { return x * sigmoidf_(x); }
;     __device__ __forceinline__ void operator()(const f32x4 (&acc)[2][2][4][2], const Unit& u, int wr, int wc, int fr, int fq) const {
;         const int row0 = u.pm * BM + wr * 64 + fr, col0 = u.pn * 128 + wc * 32 + 8 * fq;
; #pragma unroll
;         for (int ai = 0; ai < 2; ++ai)
; #pragma unroll
;             for (int m = 0; m < 4; ++m) {
;                 const int row = row0 + ai * HALF + m * 16;
;                 const float rs = rsqrtf(ss[row] * (1.f / DM) + EPS);
;                 float h[8];
; #pragma unroll
;                 for (int n = 0; n < 2; ++n)
; #pragma unroll
;                     for (int j = 0; j < 4; ++j) { const float gg = acc[ai][0][m][n][j] * rs, uu = acc[ai][1][m][n][j] * rs; h[4 * n + j] = siluf_(gg) * uu; }
;                 u32x4 w; w.x = cvt_pk(h[0], h[1]); w.y = cvt_pk(h[2], h[3]); w.z = cvt_pk(h[4], h[5]); w.w = cvt_pk(h[6], h[7]);
;                 *(u32x4*)(H + (size_t)row * DFF + col0) = w;
	v_cvt_pk_bf16_f32 v172, v108, v109
	v_cvt_pk_bf16_f32 v173, v110, v111
	v_cvt_pk_bf16_f32 v174, v100, v101
	v_cvt_pk_bf16_f32 v175, v102, v103
	v_lshl_add_u64 v[184:185], v[184:185], 0, v[188:189]
	global_store_dwordx4 v[184:185], v[172:175], off sc1
	v_fmamk_f32 v180, v163, 0x3a800000, v217
	v_cmp_gt_f32_e32 vcc, s15, v180
	v_mul_f32_e32 v181, 0x4b800000, v180
	s_nop 0
	v_cndmask_b32_e32 v180, v180, v181, vcc
	v_rsq_f32_e32 v180, v180
	v_add_u32_e32 v182, 32, v138
	v_mul_f32_e32 v181, 0x45800000, v180
	v_cndmask_b32_e32 v180, v180, v181, vcc
	v_mul_f32_e32 v92, v92, v180
	v_mul_f32_e32 v88, v88, v180
	v_mul_f32_e32 v93, v93, v180
	v_mul_f32_e32 v89, v89, v180
	v_mul_f32_e32 v94, v94, v180
	v_mul_f32_e32 v90, v90, v180
	v_mul_f32_e32 v95, v95, v180
	v_mul_f32_e32 v91, v91, v180
	v_mul_f32_e32 v84, v84, v180
	v_mul_f32_e32 v80, v80, v180
	v_mul_f32_e32 v85, v85, v180
	v_mul_f32_e32 v81, v81, v180
	v_mul_f32_e32 v86, v86, v180
	v_mul_f32_e32 v82, v82, v180
	v_mul_f32_e32 v87, v87, v180
	v_mul_f32_e32 v83, v83, v180
	v_mul_f32_e32 v172, 0xbfb8aa3b, v92
	v_mul_f32_e32 v173, 0xbfb8aa3b, v93
	v_mul_f32_e32 v174, 0xbfb8aa3b, v94
	v_mul_f32_e32 v175, 0xbfb8aa3b, v95
	v_mul_f32_e32 v176, 0xbfb8aa3b, v84
	v_mul_f32_e32 v177, 0xbfb8aa3b, v85
	v_mul_f32_e32 v178, 0xbfb8aa3b, v86
	v_mul_f32_e32 v179, 0xbfb8aa3b, v87
	v_exp_f32_e32 v172, v172
	v_exp_f32_e32 v173, v173
	v_exp_f32_e32 v174, v174
	v_exp_f32_e32 v175, v175
	v_exp_f32_e32 v176, v176
	v_exp_f32_e32 v177, v177
	v_exp_f32_e32 v178, v178
	v_exp_f32_e32 v179, v179
	v_add_f32_e32 v172, 1.0, v172
	v_add_f32_e32 v173, 1.0, v173
	v_add_f32_e32 v174, 1.0, v174
	v_add_f32_e32 v175, 1.0, v175
	v_add_f32_e32 v176, 1.0, v176
	v_add_f32_e32 v177, 1.0, v177
	v_add_f32_e32 v178, 1.0, v178
	v_add_f32_e32 v179, 1.0, v179
	v_rcp_f32_e32 v172, v172
	v_rcp_f32_e32 v173, v173
	v_rcp_f32_e32 v174, v174
	v_rcp_f32_e32 v175, v175
	v_rcp_f32_e32 v176, v176
	v_rcp_f32_e32 v177, v177
	v_rcp_f32_e32 v178, v178
	v_rcp_f32_e32 v179, v179
	v_mul_f32_e32 v92, v92, v172
	v_mul_f32_e32 v93, v93, v173
	v_mul_f32_e32 v94, v94, v174
	v_mul_f32_e32 v95, v95, v175
	v_mul_f32_e32 v84, v84, v176
	v_mul_f32_e32 v85, v85, v177
	v_mul_f32_e32 v86, v86, v178
	v_mul_f32_e32 v87, v87, v179
	v_mul_f32_e32 v92, v88, v92
	v_mul_f32_e32 v93, v89, v93
	v_mul_f32_e32 v94, v90, v94
	v_mul_f32_e32 v95, v91, v95
	v_mul_f32_e32 v84, v80, v84
	v_mul_f32_e32 v85, v81, v85
	v_mul_f32_e32 v86, v82, v86
	v_mul_f32_e32 v87, v83, v87
	v_mad_i64_i32 v[184:185], s[2:3], v182, s64, v[186:187]
	v_cvt_pk_bf16_f32 v172, v92, v93
	v_cvt_pk_bf16_f32 v173, v94, v95
	v_cvt_pk_bf16_f32 v174, v84, v85
	v_cvt_pk_bf16_f32 v175, v86, v87
	v_lshl_add_u64 v[184:185], v[184:185], 0, v[188:189]
	global_store_dwordx4 v[184:185], v[172:175], off sc1
	v_fmamk_f32 v180, v164, 0x3a800000, v217
	v_cmp_gt_f32_e32 vcc, s15, v180
	v_mul_f32_e32 v181, 0x4b800000, v180
	s_nop 0
	v_cndmask_b32_e32 v180, v180, v181, vcc
	v_rsq_f32_e32 v180, v180
	v_add_u32_e32 v182, 48, v138
	v_mul_f32_e32 v181, 0x45800000, v180
	v_cndmask_b32_e32 v180, v180, v181, vcc
	v_mul_f32_e32 v76, v76, v180
	v_mul_f32_e32 v72, v72, v180
	v_mul_f32_e32 v77, v77, v180
	v_mul_f32_e32 v73, v73, v180
	v_mul_f32_e32 v78, v78, v180
	v_mul_f32_e32 v74, v74, v180
	v_mul_f32_e32 v79, v79, v180
	v_mul_f32_e32 v75, v75, v180
	v_mul_f32_e32 v68, v68, v180
	v_mul_f32_e32 v64, v64, v180
	v_mul_f32_e32 v69, v69, v180
	v_mul_f32_e32 v65, v65, v180
	v_mul_f32_e32 v70, v70, v180
	v_mul_f32_e32 v66, v66, v180
	v_mul_f32_e32 v71, v71, v180
	v_mul_f32_e32 v67, v67, v180
	v_mul_f32_e32 v172, 0xbfb8aa3b, v76
	v_mul_f32_e32 v173, 0xbfb8aa3b, v77
	v_mul_f32_e32 v174, 0xbfb8aa3b, v78
	v_mul_f32_e32 v175, 0xbfb8aa3b, v79
	v_mul_f32_e32 v176, 0xbfb8aa3b, v68
	v_mul_f32_e32 v177, 0xbfb8aa3b, v69
	v_mul_f32_e32 v178, 0xbfb8aa3b, v70
	v_mul_f32_e32 v179, 0xbfb8aa3b, v71
	v_exp_f32_e32 v172, v172
	v_exp_f32_e32 v173, v173
	v_exp_f32_e32 v174, v174
	v_exp_f32_e32 v175, v175
	v_exp_f32_e32 v176, v176
	v_exp_f32_e32 v177, v177
	v_exp_f32_e32 v178, v178
	v_exp_f32_e32 v179, v179
	v_add_f32_e32 v172, 1.0, v172
	v_add_f32_e32 v173, 1.0, v173
	v_add_f32_e32 v174, 1.0, v174
	v_add_f32_e32 v175, 1.0, v175
	v_add_f32_e32 v176, 1.0, v176
	v_add_f32_e32 v177, 1.0, v177
	v_add_f32_e32 v178, 1.0, v178
	v_add_f32_e32 v179, 1.0, v179
	v_rcp_f32_e32 v172, v172
	v_rcp_f32_e32 v173, v173
	v_rcp_f32_e32 v174, v174
	v_rcp_f32_e32 v175, v175
	v_rcp_f32_e32 v176, v176
	v_rcp_f32_e32 v177, v177
	v_rcp_f32_e32 v178, v178
	v_rcp_f32_e32 v179, v179
	v_mul_f32_e32 v76, v76, v172
	v_mul_f32_e32 v77, v77, v173
	v_mul_f32_e32 v78, v78, v174
	v_mul_f32_e32 v79, v79, v175
	v_mul_f32_e32 v68, v68, v176
	v_mul_f32_e32 v69, v69, v177
	v_mul_f32_e32 v70, v70, v178
	v_mul_f32_e32 v71, v71, v179
	v_mul_f32_e32 v76, v72, v76
	v_mul_f32_e32 v77, v73, v77
	v_mul_f32_e32 v78, v74, v78
	v_mul_f32_e32 v79, v75, v79
	v_mul_f32_e32 v68, v64, v68
	v_mul_f32_e32 v69, v65, v69
	v_mul_f32_e32 v70, v66, v70
	v_mul_f32_e32 v71, v67, v71
	v_mad_i64_i32 v[184:185], s[2:3], v182, s64, v[186:187]
	v_cvt_pk_bf16_f32 v172, v76, v77
	v_cvt_pk_bf16_f32 v173, v78, v79
	v_cvt_pk_bf16_f32 v174, v68, v69
	v_cvt_pk_bf16_f32 v175, v70, v71
	v_lshl_add_u64 v[184:185], v[184:185], 0, v[188:189]
	global_store_dwordx4 v[184:185], v[172:175], off sc1
	v_fmamk_f32 v180, v165, 0x3a800000, v217
	v_cmp_gt_f32_e32 vcc, s15, v180
	v_mul_f32_e32 v181, 0x4b800000, v180
	s_nop 0
	v_cndmask_b32_e32 v180, v180, v181, vcc
	v_rsq_f32_e32 v180, v180
	v_add_u32_e32 v182, 128, v138
	v_mul_f32_e32 v181, 0x45800000, v180
	v_cndmask_b32_e32 v180, v180, v181, vcc
	v_mul_f32_e32 v60, v60, v180
	v_mul_f32_e32 v56, v56, v180
; DI unsigned cvt_pk(float lo, float hi) { unsigned r; asm("v_cvt_pk_bf16_f32 %0, %1, %2" : "=v"(r) : "v"(lo), "v"(hi)); return r; }
; DI float siluf_(float x) { return x * sigmoidf_(x); }
;     __device__ __forceinline__ void operator()(const f32x4 (&acc)[2][2][4][2], const Unit& u, int wr, int wc, int fr, int fq) const {
;         const int row0 = u.pm * BM + wr * 64 + fr, col0 = u.pn * 128 + wc * 32 + 8 * fq;
; #pragma unroll
;         for (int ai = 0; ai < 2; ++ai)
; #pragma unroll
;             for (int m = 0; m < 4; ++m) {
;                 const int row = row0 + ai * HALF + m * 16;
;                 const float rs = rsqrtf(ss[row] * (1.f / DM) + EPS);
;                 float h[8];
; #pragma unroll
;                 for (int n = 0; n < 2; ++n)
; #pragma unroll
;                     for (int j = 0; j < 4; ++j) { const float gg = acc[ai][0][m][n][j] * rs, uu = acc[ai][1][m][n][j] * rs; h[4 * n + j] = siluf_(gg) * uu; }
;                 u32x4 w; w.x = cvt_pk(h[0], h[1]); w.y = cvt_pk(h[2], h[3]); w.z = cvt_pk(h[4], h[5]); w.w = cvt_pk(h[6], h[7]);
;                 *(u32x4*)(H + (size_t)row * DFF + col0) = w;
	v_mul_f32_e32 v61, v61, v180
	v_mul_f32_e32 v57, v57, v180
	v_mul_f32_e32 v62, v62, v180
	v_mul_f32_e32 v58, v58, v180
	v_mul_f32_e32 v63, v63, v180
	v_mul_f32_e32 v59, v59, v180
	v_mul_f32_e32 v52, v52, v180
	v_mul_f32_e32 v48, v48, v180
	v_mul_f32_e32 v53, v53, v180
	v_mul_f32_e32 v49, v49, v180
	v_mul_f32_e32 v54, v54, v180
	v_mul_f32_e32 v50, v50, v180
	v_mul_f32_e32 v55, v55, v180
	v_mul_f32_e32 v51, v51, v180
	v_mul_f32_e32 v172, 0xbfb8aa3b, v60
	v_mul_f32_e32 v173, 0xbfb8aa3b, v61
	v_mul_f32_e32 v174, 0xbfb8aa3b, v62
	v_mul_f32_e32 v175, 0xbfb8aa3b, v63
	v_mul_f32_e32 v176, 0xbfb8aa3b, v52
	v_mul_f32_e32 v177, 0xbfb8aa3b, v53
	v_mul_f32_e32 v178, 0xbfb8aa3b, v54
	v_mul_f32_e32 v179, 0xbfb8aa3b, v55
	v_exp_f32_e32 v172, v172
	v_exp_f32_e32 v173, v173
	v_exp_f32_e32 v174, v174
	v_exp_f32_e32 v175, v175
	v_exp_f32_e32 v176, v176
	v_exp_f32_e32 v177, v177
	v_exp_f32_e32 v178, v178
	v_exp_f32_e32 v179, v179
	v_add_f32_e32 v172, 1.0, v172
	v_add_f32_e32 v173, 1.0, v173
	v_add_f32_e32 v174, 1.0, v174
	v_add_f32_e32 v175, 1.0, v175
	v_add_f32_e32 v176, 1.0, v176
	v_add_f32_e32 v177, 1.0, v177
	v_add_f32_e32 v178, 1.0, v178
	v_add_f32_e32 v179, 1.0, v179
	v_rcp_f32_e32 v172, v172
	v_rcp_f32_e32 v173, v173
	v_rcp_f32_e32 v174, v174
	v_rcp_f32_e32 v175, v175
	v_rcp_f32_e32 v176, v176
	v_rcp_f32_e32 v177, v177
	v_rcp_f32_e32 v178, v178
	v_rcp_f32_e32 v179, v179
	v_mul_f32_e32 v60, v60, v172
	v_mul_f32_e32 v61, v61, v173
	v_mul_f32_e32 v62, v62, v174
	v_mul_f32_e32 v63, v63, v175
	v_mul_f32_e32 v52, v52, v176
	v_mul_f32_e32 v53, v53, v177
	v_mul_f32_e32 v54, v54, v178
	v_mul_f32_e32 v55, v55, v179
	v_mul_f32_e32 v60, v56, v60
	v_mul_f32_e32 v61, v57, v61
	v_mul_f32_e32 v62, v58, v62
	v_mul_f32_e32 v63, v59, v63
	v_mul_f32_e32 v52, v48, v52
	v_mul_f32_e32 v53, v49, v53
	v_mul_f32_e32 v54, v50, v54
	v_mul_f32_e32 v55, v51, v55
	v_mad_i64_i32 v[184:185], s[2:3], v182, s64, v[186:187]
	v_cvt_pk_bf16_f32 v172, v60, v61
	v_cvt_pk_bf16_f32 v173, v62, v63
	v_cvt_pk_bf16_f32 v174, v52, v53
	v_cvt_pk_bf16_f32 v175, v54, v55
	v_lshl_add_u64 v[184:185], v[184:185], 0, v[188:189]
	global_store_dwordx4 v[184:185], v[172:175], off sc1
	v_fmamk_f32 v180, v166, 0x3a800000, v217
	v_cmp_gt_f32_e32 vcc, s15, v180
	v_mul_f32_e32 v181, 0x4b800000, v180
	s_nop 0
	v_cndmask_b32_e32 v180, v180, v181, vcc
	v_rsq_f32_e32 v180, v180
	v_add_u32_e32 v182, 144, v138
	v_mul_f32_e32 v181, 0x45800000, v180
	v_cndmask_b32_e32 v180, v180, v181, vcc
	v_mul_f32_e32 v44, v44, v180
	v_mul_f32_e32 v40, v40, v180
	v_mul_f32_e32 v45, v45, v180
	v_mul_f32_e32 v41, v41, v180
	v_mul_f32_e32 v46, v46, v180
	v_mul_f32_e32 v42, v42, v180
	v_mul_f32_e32 v47, v47, v180
	v_mul_f32_e32 v43, v43, v180
	v_mul_f32_e32 v36, v36, v180
	v_mul_f32_e32 v32, v32, v180
	v_mul_f32_e32 v37, v37, v180
	v_mul_f32_e32 v33, v33, v180
	v_mul_f32_e32 v38, v38, v180
	v_mul_f32_e32 v34, v34, v180
	v_mul_f32_e32 v39, v39, v180
	v_mul_f32_e32 v35, v35, v180
	v_mul_f32_e32 v172, 0xbfb8aa3b, v44
	v_mul_f32_e32 v173, 0xbfb8aa3b, v45
	v_mul_f32_e32 v174, 0xbfb8aa3b, v46
	v_mul_f32_e32 v175, 0xbfb8aa3b, v47
	v_mul_f32_e32 v176, 0xbfb8aa3b, v36
	v_mul_f32_e32 v177, 0xbfb8aa3b, v37
	v_mul_f32_e32 v178, 0xbfb8aa3b, v38
	v_mul_f32_e32 v179, 0xbfb8aa3b, v39
	v_exp_f32_e32 v172, v172
	v_exp_f32_e32 v173, v173
	v_exp_f32_e32 v174, v174
	v_exp_f32_e32 v175, v175
	v_exp_f32_e32 v176, v176
	v_exp_f32_e32 v177, v177
	v_exp_f32_e32 v178, v178
	v_exp_f32_e32 v179, v179
	v_add_f32_e32 v172, 1.0, v172
	v_add_f32_e32 v173, 1.0, v173
	v_add_f32_e32 v174, 1.0, v174
	v_add_f32_e32 v175, 1.0, v175
	v_add_f32_e32 v176, 1.0, v176
	v_add_f32_e32 v177, 1.0, v177
	v_add_f32_e32 v178, 1.0, v178
	v_add_f32_e32 v179, 1.0, v179
	v_rcp_f32_e32 v172, v172
	v_rcp_f32_e32 v173, v173
	v_rcp_f32_e32 v174, v174
	v_rcp_f32_e32 v175, v175
	v_rcp_f32_e32 v176, v176
	v_rcp_f32_e32 v177, v177
	v_rcp_f32_e32 v178, v178
	v_rcp_f32_e32 v179, v179
	v_mul_f32_e32 v44, v44, v172
	v_mul_f32_e32 v45, v45, v173
	v_mul_f32_e32 v46, v46, v174
	v_mul_f32_e32 v47, v47, v175
	v_mul_f32_e32 v36, v36, v176
	v_mul_f32_e32 v37, v37, v177
	v_mul_f32_e32 v38, v38, v178
	v_mul_f32_e32 v39, v39, v179
	v_mul_f32_e32 v44, v40, v44
	v_mul_f32_e32 v45, v41, v45
	v_mul_f32_e32 v46, v42, v46
	v_mul_f32_e32 v47, v43, v47
	v_mul_f32_e32 v36, v32, v36
	v_mul_f32_e32 v37, v33, v37
	v_mul_f32_e32 v38, v34, v38
	v_mul_f32_e32 v39, v35, v39
	v_mad_i64_i32 v[184:185], s[2:3], v182, s64, v[186:187]
	v_cvt_pk_bf16_f32 v172, v44, v45
	v_cvt_pk_bf16_f32 v173, v46, v47
	v_cvt_pk_bf16_f32 v174, v36, v37
	v_cvt_pk_bf16_f32 v175, v38, v39
	v_lshl_add_u64 v[184:185], v[184:185], 0, v[188:189]
	global_store_dwordx4 v[184:185], v[172:175], off sc1
	v_fmamk_f32 v180, v167, 0x3a800000, v217
	v_cmp_gt_f32_e32 vcc, s15, v180
	v_mul_f32_e32 v181, 0x4b800000, v180
	s_nop 0
	v_cndmask_b32_e32 v180, v180, v181, vcc
	v_rsq_f32_e32 v180, v180
	v_add_u32_e32 v182, 160, v138
; DI unsigned cvt_pk(float lo, float hi) { unsigned r; asm("v_cvt_pk_bf16_f32 %0, %1, %2" : "=v"(r) : "v"(lo), "v"(hi)); return r; }
; DI float siluf_(float x) { return x * sigmoidf_(x); }
;     __device__ __forceinline__ void operator()(const f32x4 (&acc)[2][2][4][2], const Unit& u, int wr, int wc, int fr, int fq) const {
;         const int row0 = u.pm * BM + wr * 64 + fr, col0 = u.pn * 128 + wc * 32 + 8 * fq;
; #pragma unroll
;         for (int ai = 0; ai < 2; ++ai)
; #pragma unroll
;             for (int m = 0; m < 4; ++m) {
;                 const int row = row0 + ai * HALF + m * 16;
;                 const float rs = rsqrtf(ss[row] * (1.f / DM) + EPS);
;                 float h[8];
; #pragma unroll
;                 for (int n = 0; n < 2; ++n)
; #pragma unroll
;                     for (int j = 0; j < 4; ++j) { const float gg = acc[ai][0][m][n][j] * rs, uu = acc[ai][1][m][n][j] * rs; h[4 * n + j] = siluf_(gg) * uu; }
;                 u32x4 w; w.x = cvt_pk(h[0], h[1]); w.y = cvt_pk(h[2], h[3]); w.z = cvt_pk(h[4], h[5]); w.w = cvt_pk(h[6], h[7]);
;                 *(u32x4*)(H + (size_t)row * DFF + col0) = w;
	v_mul_f32_e32 v181, 0x45800000, v180
	v_cndmask_b32_e32 v180, v180, v181, vcc
	v_mul_f32_e32 v28, v28, v180
	v_mul_f32_e32 v24, v24, v180
	v_mul_f32_e32 v29, v29, v180
	v_mul_f32_e32 v25, v25, v180
	v_mul_f32_e32 v30, v30, v180
	v_mul_f32_e32 v26, v26, v180
	v_mul_f32_e32 v31, v31, v180
	v_mul_f32_e32 v27, v27, v180
	v_mul_f32_e32 v20, v20, v180
	v_mul_f32_e32 v16, v16, v180
	v_mul_f32_e32 v21, v21, v180
	v_mul_f32_e32 v17, v17, v180
	v_mul_f32_e32 v22, v22, v180
	v_mul_f32_e32 v18, v18, v180
	v_mul_f32_e32 v23, v23, v180
	v_mul_f32_e32 v19, v19, v180
	v_mul_f32_e32 v172, 0xbfb8aa3b, v28
	v_mul_f32_e32 v173, 0xbfb8aa3b, v29
	v_mul_f32_e32 v174, 0xbfb8aa3b, v30
	v_mul_f32_e32 v175, 0xbfb8aa3b, v31
	v_mul_f32_e32 v176, 0xbfb8aa3b, v20
	v_mul_f32_e32 v177, 0xbfb8aa3b, v21
	v_mul_f32_e32 v178, 0xbfb8aa3b, v22
	v_mul_f32_e32 v179, 0xbfb8aa3b, v23
	v_exp_f32_e32 v172, v172
	v_exp_f32_e32 v173, v173
	v_exp_f32_e32 v174, v174
	v_exp_f32_e32 v175, v175
	v_exp_f32_e32 v176, v176
	v_exp_f32_e32 v177, v177
	v_exp_f32_e32 v178, v178
	v_exp_f32_e32 v179, v179
	v_add_f32_e32 v172, 1.0, v172
	v_add_f32_e32 v173, 1.0, v173
	v_add_f32_e32 v174, 1.0, v174
	v_add_f32_e32 v175, 1.0, v175
	v_add_f32_e32 v176, 1.0, v176
	v_add_f32_e32 v177, 1.0, v177
	v_add_f32_e32 v178, 1.0, v178
	v_add_f32_e32 v179, 1.0, v179
	v_rcp_f32_e32 v172, v172
	v_rcp_f32_e32 v173, v173
	v_rcp_f32_e32 v174, v174
	v_rcp_f32_e32 v175, v175
	v_rcp_f32_e32 v176, v176
	v_rcp_f32_e32 v177, v177
	v_rcp_f32_e32 v178, v178
	v_rcp_f32_e32 v179, v179
	v_mul_f32_e32 v28, v28, v172
	v_mul_f32_e32 v29, v29, v173
	v_mul_f32_e32 v30, v30, v174
	v_mul_f32_e32 v31, v31, v175
	v_mul_f32_e32 v20, v20, v176
	v_mul_f32_e32 v21, v21, v177
	v_mul_f32_e32 v22, v22, v178
	v_mul_f32_e32 v23, v23, v179
	v_mul_f32_e32 v28, v24, v28
	v_mul_f32_e32 v29, v25, v29
	v_mul_f32_e32 v30, v26, v30
	v_mul_f32_e32 v31, v27, v31
	v_mul_f32_e32 v20, v16, v20
	v_mul_f32_e32 v21, v17, v21
	v_mul_f32_e32 v22, v18, v22
	v_mul_f32_e32 v23, v19, v23
	v_mad_i64_i32 v[184:185], s[2:3], v182, s64, v[186:187]
	v_cvt_pk_bf16_f32 v172, v28, v29
	v_cvt_pk_bf16_f32 v173, v30, v31
	v_cvt_pk_bf16_f32 v174, v20, v21
	v_cvt_pk_bf16_f32 v175, v22, v23
	v_lshl_add_u64 v[184:185], v[184:185], 0, v[188:189]
	global_store_dwordx4 v[184:185], v[172:175], off sc1
	v_fmamk_f32 v180, v168, 0x3a800000, v217
	v_cmp_gt_f32_e32 vcc, s15, v180
	v_mul_f32_e32 v181, 0x4b800000, v180
	s_nop 0
	v_cndmask_b32_e32 v180, v180, v181, vcc
	v_rsq_f32_e32 v180, v180
	v_add_u32_e32 v182, 176, v138
	v_mul_f32_e32 v181, 0x45800000, v180
	v_cndmask_b32_e32 v180, v180, v181, vcc
	v_mul_f32_e32 v12, v12, v180
	v_mul_f32_e32 v8, v8, v180
	v_mul_f32_e32 v13, v13, v180
	v_mul_f32_e32 v9, v9, v180
	v_mul_f32_e32 v14, v14, v180
	v_mul_f32_e32 v10, v10, v180
	v_mul_f32_e32 v15, v15, v180
	v_mul_f32_e32 v11, v11, v180
	v_mul_f32_e32 v4, v4, v180
	v_mul_f32_e32 v0, v0, v180
	v_mul_f32_e32 v5, v5, v180
	v_mul_f32_e32 v1, v1, v180
	v_mul_f32_e32 v6, v6, v180
	v_mul_f32_e32 v2, v2, v180
	v_mul_f32_e32 v7, v7, v180
	v_mul_f32_e32 v3, v3, v180
	v_mul_f32_e32 v172, 0xbfb8aa3b, v12
	v_mul_f32_e32 v173, 0xbfb8aa3b, v13
	v_mul_f32_e32 v174, 0xbfb8aa3b, v14
	v_mul_f32_e32 v175, 0xbfb8aa3b, v15
	v_mul_f32_e32 v176, 0xbfb8aa3b, v4
	v_mul_f32_e32 v177, 0xbfb8aa3b, v5
	v_mul_f32_e32 v178, 0xbfb8aa3b, v6
	v_mul_f32_e32 v179, 0xbfb8aa3b, v7
	v_exp_f32_e32 v172, v172
	v_exp_f32_e32 v173, v173
	v_exp_f32_e32 v174, v174
	v_exp_f32_e32 v175, v175
	v_exp_f32_e32 v176, v176
	v_exp_f32_e32 v177, v177
	v_exp_f32_e32 v178, v178
	v_exp_f32_e32 v179, v179
	v_add_f32_e32 v172, 1.0, v172
	v_add_f32_e32 v173, 1.0, v173
	v_add_f32_e32 v174, 1.0, v174
	v_add_f32_e32 v175, 1.0, v175
	v_add_f32_e32 v176, 1.0, v176
	v_add_f32_e32 v177, 1.0, v177
	v_add_f32_e32 v178, 1.0, v178
	v_add_f32_e32 v179, 1.0, v179
	v_rcp_f32_e32 v172, v172
	v_rcp_f32_e32 v173, v173
	v_rcp_f32_e32 v174, v174
	v_rcp_f32_e32 v175, v175
	v_rcp_f32_e32 v176, v176
	v_rcp_f32_e32 v177, v177
	v_rcp_f32_e32 v178, v178
	v_rcp_f32_e32 v179, v179
	v_mul_f32_e32 v12, v12, v172
	v_mul_f32_e32 v13, v13, v173
	v_mul_f32_e32 v14, v14, v174
	v_mul_f32_e32 v15, v15, v175
	v_mul_f32_e32 v4, v4, v176
	v_mul_f32_e32 v5, v5, v177
	v_mul_f32_e32 v6, v6, v178
	v_mul_f32_e32 v7, v7, v179
	v_mul_f32_e32 v12, v8, v12
	v_mul_f32_e32 v13, v9, v13
	v_mul_f32_e32 v14, v10, v14
	v_mul_f32_e32 v15, v11, v15
	v_mul_f32_e32 v4, v0, v4
	v_mul_f32_e32 v5, v1, v5
	v_mul_f32_e32 v6, v2, v6
	v_mul_f32_e32 v7, v3, v7
	v_mad_i64_i32 v[184:185], s[2:3], v182, s64, v[186:187]
	v_cvt_pk_bf16_f32 v172, v12, v13
	v_cvt_pk_bf16_f32 v173, v14, v15
	v_cvt_pk_bf16_f32 v174, v4, v5
	v_cvt_pk_bf16_f32 v175, v6, v7
	v_lshl_add_u64 v[184:185], v[184:185], 0, v[188:189]
	global_store_dwordx4 v[184:185], v[172:175], off sc1
	s_mov_b64 s[2:3], -1
	s_andn2_b64 vcc, exec, s[4:5]
	s_cbranch_vccnz .LBB0_286
	s_andn2_b64 vcc, exec, s[6:7]
	s_cbranch_vccnz .LBB0_285
	s_barrier
	s_branch .LBB0_285

; DI unsigned cvt_pk(float lo, float hi) { unsigned r; asm("v_cvt_pk_bf16_f32 %0, %1, %2" : "=v"(r) : "v"(lo), "v"(hi)); return r; }
;     __device__ __forceinline__ void operator()(const f32x4 (&acc)[2][2][4][2], const Unit& u, int wr, int wc, int fr, int fq) const {
;         const int row0 = u.pm * BM + wr * 64 + fr, col0 = u.pn * BM + wc * 32 + 8 * fq;
; #pragma unroll
;         for (int ai = 0; ai < 2; ++ai)
; #pragma unroll
;             for (int m = 0; m < 4; ++m) {
;                 const int row = row0 + ai * HALF + m * 16;
;                 const float rs = rsqrtf(ss[row] * (1.f / DM) + EPS);
; #pragma unroll
;                 for (int bj = 0; bj < 2; ++bj) {
;                     const f32x4 v0 = acc[ai][bj][m][0] * rs, v1 = acc[ai][bj][m][1] * rs;
;                     u32x4 w; w.x = cvt_pk(v0[0], v0[1]); w.y = cvt_pk(v0[2], v0[3]); w.z = cvt_pk(v1[0], v1[1]); w.w = cvt_pk(v1[2], v1[3]);
;                     *(u32x4*)(O + (size_t)row * ldc + col0 + bj * HALF) = w;
;                 }
.LBB0_542:
	v_lshl_add_u32 v138, s39, 8, v142
	v_ashrrev_i32_e32 v139, 31, v138
	v_lshl_add_u64 v[140:141], v[138:139], 2, s[4:5]
	global_load_dword v139, v[140:141], off
	global_load_dword v162, v[140:141], off offset:64
	global_load_dword v163, v[140:141], off offset:128
	global_load_dword v164, v[140:141], off offset:192
	global_load_dword v165, v[140:141], off offset:512
	global_load_dword v166, v[140:141], off offset:576
	global_load_dword v167, v[140:141], off offset:640
	global_load_dword v168, v[140:141], off offset:704
	s_mov_b32 s11, 0x800000
	v_lshl_or_b32 v156, s38, 8, v154
	v_ashrrev_i32_e32 v157, 31, v156
	s_waitcnt vmcnt(0)
	v_fmamk_f32 v139, v139, 0x3a800000, v217
	v_cmp_gt_f32_e32 vcc, s11, v139
	v_mul_f32_e32 v158, 0x4b800000, v139
	s_nop 0
	v_cndmask_b32_e32 v139, v139, v158, vcc
	v_rsq_f32_e32 v139, v139
	s_nop 0
	v_mul_f32_e32 v158, 0x45800000, v139
	v_cndmask_b32_e32 v158, v139, v158, vcc
	v_pk_mul_f32 v[126:127], v[126:127], v[158:159] op_sel_hi:[1,0]
	v_pk_mul_f32 v[124:125], v[124:125], v[158:159] op_sel_hi:[1,0]
	v_pk_mul_f32 v[120:121], v[120:121], v[158:159] op_sel_hi:[1,0]
	v_pk_mul_f32 v[122:123], v[122:123], v[158:159] op_sel_hi:[1,0]
	v_cvt_pk_bf16_f32 v124, v124, v125
	v_cvt_pk_bf16_f32 v125, v126, v127
	v_cvt_pk_bf16_f32 v126, v120, v121
	v_mov_b64_e32 v[120:121], s[2:3]
	v_cvt_pk_bf16_f32 v127, v122, v123
	v_mad_i64_i32 v[160:161], s[20:21], v138, s64, v[120:121]
	v_lshlrev_b64 v[122:123], 1, v[156:157]
	v_lshl_add_u64 v[156:157], v[160:161], 0, v[122:123]
	global_store_dwordx4 v[156:157], v[124:127], off sc1
	v_pk_mul_f32 v[118:119], v[118:119], v[158:159] op_sel_hi:[1,0]
	v_pk_mul_f32 v[116:117], v[116:117], v[158:159] op_sel_hi:[1,0]
	v_pk_mul_f32 v[124:125], v[114:115], v[158:159] op_sel_hi:[1,0]
	v_pk_mul_f32 v[114:115], v[112:113], v[158:159] op_sel_hi:[1,0]
	v_cvt_pk_bf16_f32 v112, v116, v117
	v_cvt_pk_bf16_f32 v113, v118, v119
	s_nop 0
	v_cvt_pk_bf16_f32 v114, v114, v115
	v_cvt_pk_bf16_f32 v115, v124, v125
	global_store_dwordx4 v[156:157], v[112:115], off offset:256 sc1
	s_nop 0
	s_nop 0
	v_or_b32_e32 v113, 16, v138
	v_mov_b32_e32 v112, v162
	v_fmamk_f32 v112, v112, 0x3a800000, v217
	v_cmp_gt_f32_e32 vcc, s11, v112
	v_mul_f32_e32 v114, 0x4b800000, v112
	s_nop 0
	v_cndmask_b32_e32 v112, v112, v114, vcc
	v_rsq_f32_e32 v112, v112
	s_nop 0
	v_mul_f32_e32 v114, 0x45800000, v112
	v_cndmask_b32_e32 v112, v112, v114, vcc
	v_pk_mul_f32 v[108:109], v[108:109], v[112:113] op_sel_hi:[1,0]
	v_pk_mul_f32 v[114:115], v[106:107], v[112:113] op_sel_hi:[1,0]
	v_pk_mul_f32 v[106:107], v[104:105], v[112:113] op_sel_hi:[1,0]
	v_cvt_pk_bf16_f32 v104, v108, v109
	v_mad_i64_i32 v[108:109], s[20:21], v113, s64, v[120:121]
	v_pk_mul_f32 v[110:111], v[110:111], v[112:113] op_sel_hi:[1,0]
	v_lshl_add_u64 v[108:109], v[108:109], 0, v[122:123]
	v_cvt_pk_bf16_f32 v105, v110, v111
	v_cvt_pk_bf16_f32 v106, v106, v107
	v_cvt_pk_bf16_f32 v107, v114, v115
	global_store_dwordx4 v[108:109], v[104:107], off sc1
	v_pk_mul_f32 v[102:103], v[102:103], v[112:113] op_sel_hi:[1,0]
	v_pk_mul_f32 v[100:101], v[100:101], v[112:113] op_sel_hi:[1,0]
	v_pk_mul_f32 v[104:105], v[98:99], v[112:113] op_sel_hi:[1,0]
	v_pk_mul_f32 v[98:99], v[96:97], v[112:113] op_sel_hi:[1,0]
	v_cvt_pk_bf16_f32 v96, v100, v101
	v_cvt_pk_bf16_f32 v97, v102, v103
	s_nop 0
	v_cvt_pk_bf16_f32 v98, v98, v99
	v_cvt_pk_bf16_f32 v99, v104, v105
	global_store_dwordx4 v[108:109], v[96:99], off offset:256 sc1
	s_nop 0
	s_nop 0
	v_or_b32_e32 v97, 32, v138
	v_mov_b32_e32 v96, v163
	v_fmamk_f32 v96, v96, 0x3a800000, v217
	v_cmp_gt_f32_e32 vcc, s11, v96
	v_mul_f32_e32 v98, 0x4b800000, v96
	s_nop 0
	v_cndmask_b32_e32 v96, v96, v98, vcc
	v_rsq_f32_e32 v96, v96
	s_nop 0
	v_mul_f32_e32 v98, 0x45800000, v96
	v_cndmask_b32_e32 v96, v96, v98, vcc
	v_pk_mul_f32 v[92:93], v[92:93], v[96:97] op_sel_hi:[1,0]
	v_pk_mul_f32 v[98:99], v[90:91], v[96:97] op_sel_hi:[1,0]
	v_pk_mul_f32 v[90:91], v[88:89], v[96:97] op_sel_hi:[1,0]
	v_cvt_pk_bf16_f32 v88, v92, v93
	v_mad_i64_i32 v[92:93], s[20:21], v97, s64, v[120:121]
	v_pk_mul_f32 v[94:95], v[94:95], v[96:97] op_sel_hi:[1,0]
	v_lshl_add_u64 v[92:93], v[92:93], 0, v[122:123]
	v_cvt_pk_bf16_f32 v89, v94, v95
	v_cvt_pk_bf16_f32 v90, v90, v91
	v_cvt_pk_bf16_f32 v91, v98, v99
	global_store_dwordx4 v[92:93], v[88:91], off sc1
	v_pk_mul_f32 v[86:87], v[86:87], v[96:97] op_sel_hi:[1,0]
	v_pk_mul_f32 v[84:85], v[84:85], v[96:97] op_sel_hi:[1,0]
	v_pk_mul_f32 v[88:89], v[82:83], v[96:97] op_sel_hi:[1,0]
	v_pk_mul_f32 v[82:83], v[80:81], v[96:97] op_sel_hi:[1,0]
	v_cvt_pk_bf16_f32 v80, v84, v85
	v_cvt_pk_bf16_f32 v81, v86, v87
	s_nop 0
	v_cvt_pk_bf16_f32 v82, v82, v83
	v_cvt_pk_bf16_f32 v83, v88, v89
	global_store_dwordx4 v[92:93], v[80:83], off offset:256 sc1
	s_nop 0
	s_nop 0
	v_or_b32_e32 v81, 48, v138
	v_mov_b32_e32 v80, v164
	v_fmamk_f32 v80, v80, 0x3a800000, v217
	v_cmp_gt_f32_e32 vcc, s11, v80
	v_mul_f32_e32 v82, 0x4b800000, v80
	s_nop 0
	v_cndmask_b32_e32 v80, v80, v82, vcc
	v_rsq_f32_e32 v80, v80
	s_nop 0
	v_mul_f32_e32 v82, 0x45800000, v80
	v_cndmask_b32_e32 v80, v80, v82, vcc
	v_pk_mul_f32 v[76:77], v[76:77], v[80:81] op_sel_hi:[1,0]
	v_pk_mul_f32 v[82:83], v[74:75], v[80:81] op_sel_hi:[1,0]
	v_pk_mul_f32 v[74:75], v[72:73], v[80:81] op_sel_hi:[1,0]
	v_cvt_pk_bf16_f32 v72, v76, v77
	v_mad_i64_i32 v[76:77], s[20:21], v81, s64, v[120:121]
	v_pk_mul_f32 v[78:79], v[78:79], v[80:81] op_sel_hi:[1,0]
	v_lshl_add_u64 v[76:77], v[76:77], 0, v[122:123]
	v_cvt_pk_bf16_f32 v73, v78, v79
	v_cvt_pk_bf16_f32 v74, v74, v75
	v_cvt_pk_bf16_f32 v75, v82, v83
	global_store_dwordx4 v[76:77], v[72:75], off sc1
	v_pk_mul_f32 v[70:71], v[70:71], v[80:81] op_sel_hi:[1,0]
; DI unsigned cvt_pk(float lo, float hi) { unsigned r; asm("v_cvt_pk_bf16_f32 %0, %1, %2" : "=v"(r) : "v"(lo), "v"(hi)); return r; }
;     __device__ __forceinline__ void operator()(const f32x4 (&acc)[2][2][4][2], const Unit& u, int wr, int wc, int fr, int fq) const {
;         const int row0 = u.pm * BM + wr * 64 + fr, col0 = u.pn * BM + wc * 32 + 8 * fq;
; #pragma unroll
;         for (int ai = 0; ai < 2; ++ai)
; #pragma unroll
;             for (int m = 0; m < 4; ++m) {
;                 const int row = row0 + ai * HALF + m * 16;
;                 const float rs = rsqrtf(ss[row] * (1.f / DM) + EPS);
; #pragma unroll
;                 for (int bj = 0; bj < 2; ++bj) {
;                     const f32x4 v0 = acc[ai][bj][m][0] * rs, v1 = acc[ai][bj][m][1] * rs;
;                     u32x4 w; w.x = cvt_pk(v0[0], v0[1]); w.y = cvt_pk(v0[2], v0[3]); w.z = cvt_pk(v1[0], v1[1]); w.w = cvt_pk(v1[2], v1[3]);
;                     *(u32x4*)(O + (size_t)row * ldc + col0 + bj * HALF) = w;
;                 }
	v_pk_mul_f32 v[68:69], v[68:69], v[80:81] op_sel_hi:[1,0]
	v_pk_mul_f32 v[72:73], v[66:67], v[80:81] op_sel_hi:[1,0]
	v_pk_mul_f32 v[66:67], v[64:65], v[80:81] op_sel_hi:[1,0]
	v_cvt_pk_bf16_f32 v64, v68, v69
	v_cvt_pk_bf16_f32 v65, v70, v71
	s_nop 0
	v_cvt_pk_bf16_f32 v66, v66, v67
	v_cvt_pk_bf16_f32 v67, v72, v73
	global_store_dwordx4 v[76:77], v[64:67], off offset:256 sc1
	s_nop 0
	s_nop 0
	v_add_u32_e32 v65, 0x80, v138
	v_mov_b32_e32 v64, v165
	v_fmamk_f32 v64, v64, 0x3a800000, v217
	v_cmp_gt_f32_e32 vcc, s11, v64
	v_mul_f32_e32 v66, 0x4b800000, v64
	s_nop 0
	v_cndmask_b32_e32 v64, v64, v66, vcc
	v_rsq_f32_e32 v64, v64
	s_nop 0
	v_mul_f32_e32 v66, 0x45800000, v64
	v_cndmask_b32_e32 v64, v64, v66, vcc
	v_pk_mul_f32 v[60:61], v[60:61], v[64:65] op_sel_hi:[1,0]
	v_pk_mul_f32 v[66:67], v[58:59], v[64:65] op_sel_hi:[1,0]
	v_pk_mul_f32 v[58:59], v[56:57], v[64:65] op_sel_hi:[1,0]
	v_cvt_pk_bf16_f32 v56, v60, v61
	v_mad_i64_i32 v[60:61], s[20:21], v65, s64, v[120:121]
	v_pk_mul_f32 v[62:63], v[62:63], v[64:65] op_sel_hi:[1,0]
	v_lshl_add_u64 v[60:61], v[60:61], 0, v[122:123]
	v_cvt_pk_bf16_f32 v57, v62, v63
	v_cvt_pk_bf16_f32 v58, v58, v59
	v_cvt_pk_bf16_f32 v59, v66, v67
	global_store_dwordx4 v[60:61], v[56:59], off sc1
	v_pk_mul_f32 v[54:55], v[54:55], v[64:65] op_sel_hi:[1,0]
	v_pk_mul_f32 v[52:53], v[52:53], v[64:65] op_sel_hi:[1,0]
	v_pk_mul_f32 v[56:57], v[50:51], v[64:65] op_sel_hi:[1,0]
	v_pk_mul_f32 v[50:51], v[48:49], v[64:65] op_sel_hi:[1,0]
	v_cvt_pk_bf16_f32 v48, v52, v53
	v_cvt_pk_bf16_f32 v49, v54, v55
	s_nop 0
	v_cvt_pk_bf16_f32 v50, v50, v51
	v_cvt_pk_bf16_f32 v51, v56, v57
	global_store_dwordx4 v[60:61], v[48:51], off offset:256 sc1
	s_nop 0
	s_nop 0
	v_add_u32_e32 v49, 0x90, v138
	v_mov_b32_e32 v48, v166
	v_fmamk_f32 v48, v48, 0x3a800000, v217
	v_cmp_gt_f32_e32 vcc, s11, v48
	v_mul_f32_e32 v50, 0x4b800000, v48
	s_nop 0
	v_cndmask_b32_e32 v48, v48, v50, vcc
	v_rsq_f32_e32 v48, v48
	s_nop 0
	v_mul_f32_e32 v50, 0x45800000, v48
	v_cndmask_b32_e32 v48, v48, v50, vcc
	v_pk_mul_f32 v[44:45], v[44:45], v[48:49] op_sel_hi:[1,0]
	v_pk_mul_f32 v[50:51], v[42:43], v[48:49] op_sel_hi:[1,0]
	v_pk_mul_f32 v[42:43], v[40:41], v[48:49] op_sel_hi:[1,0]
	v_cvt_pk_bf16_f32 v40, v44, v45
	v_mad_i64_i32 v[44:45], s[20:21], v49, s64, v[120:121]
	v_pk_mul_f32 v[46:47], v[46:47], v[48:49] op_sel_hi:[1,0]
	v_lshl_add_u64 v[44:45], v[44:45], 0, v[122:123]
	v_cvt_pk_bf16_f32 v41, v46, v47
	v_cvt_pk_bf16_f32 v42, v42, v43
	v_cvt_pk_bf16_f32 v43, v50, v51
	global_store_dwordx4 v[44:45], v[40:43], off sc1
	v_pk_mul_f32 v[38:39], v[38:39], v[48:49] op_sel_hi:[1,0]
	v_pk_mul_f32 v[36:37], v[36:37], v[48:49] op_sel_hi:[1,0]
	v_pk_mul_f32 v[40:41], v[34:35], v[48:49] op_sel_hi:[1,0]
	v_pk_mul_f32 v[34:35], v[32:33], v[48:49] op_sel_hi:[1,0]
	v_cvt_pk_bf16_f32 v32, v36, v37
	v_cvt_pk_bf16_f32 v33, v38, v39
	s_nop 0
	v_cvt_pk_bf16_f32 v34, v34, v35
	v_cvt_pk_bf16_f32 v35, v40, v41
	global_store_dwordx4 v[44:45], v[32:35], off offset:256 sc1
	s_nop 0
	s_nop 0
	v_add_u32_e32 v33, 0xa0, v138
	v_mov_b32_e32 v32, v167
	v_fmamk_f32 v32, v32, 0x3a800000, v217
	v_cmp_gt_f32_e32 vcc, s11, v32
	v_mul_f32_e32 v34, 0x4b800000, v32
	s_nop 0
	v_cndmask_b32_e32 v32, v32, v34, vcc
	v_rsq_f32_e32 v32, v32
	s_nop 0
	v_mul_f32_e32 v34, 0x45800000, v32
	v_cndmask_b32_e32 v32, v32, v34, vcc
	v_pk_mul_f32 v[28:29], v[28:29], v[32:33] op_sel_hi:[1,0]
	v_pk_mul_f32 v[34:35], v[26:27], v[32:33] op_sel_hi:[1,0]
	v_pk_mul_f32 v[26:27], v[24:25], v[32:33] op_sel_hi:[1,0]
	v_cvt_pk_bf16_f32 v24, v28, v29
	v_mad_i64_i32 v[28:29], s[20:21], v33, s64, v[120:121]
	v_pk_mul_f32 v[30:31], v[30:31], v[32:33] op_sel_hi:[1,0]
	v_lshl_add_u64 v[28:29], v[28:29], 0, v[122:123]
	v_cvt_pk_bf16_f32 v25, v30, v31
	v_cvt_pk_bf16_f32 v26, v26, v27
	v_cvt_pk_bf16_f32 v27, v34, v35
	global_store_dwordx4 v[28:29], v[24:27], off sc1
	v_pk_mul_f32 v[22:23], v[22:23], v[32:33] op_sel_hi:[1,0]
	v_pk_mul_f32 v[20:21], v[20:21], v[32:33] op_sel_hi:[1,0]
	v_pk_mul_f32 v[24:25], v[18:19], v[32:33] op_sel_hi:[1,0]
	v_pk_mul_f32 v[18:19], v[16:17], v[32:33] op_sel_hi:[1,0]
	v_cvt_pk_bf16_f32 v16, v20, v21
	v_cvt_pk_bf16_f32 v17, v22, v23
	s_nop 0
	v_cvt_pk_bf16_f32 v18, v18, v19
	v_cvt_pk_bf16_f32 v19, v24, v25
	global_store_dwordx4 v[28:29], v[16:19], off offset:256 sc1
	s_nop 0
	s_nop 0
	v_add_u32_e32 v17, 0xb0, v138
	v_mov_b32_e32 v16, v168
	v_fmamk_f32 v16, v16, 0x3a800000, v217
	v_cmp_gt_f32_e32 vcc, s11, v16
	v_mul_f32_e32 v18, 0x4b800000, v16
	s_nop 0
	v_cndmask_b32_e32 v16, v16, v18, vcc
	v_rsq_f32_e32 v16, v16
	s_nop 0
	v_mul_f32_e32 v18, 0x45800000, v16
	v_cndmask_b32_e32 v16, v16, v18, vcc
	v_pk_mul_f32 v[12:13], v[12:13], v[16:17] op_sel_hi:[1,0]
	v_pk_mul_f32 v[18:19], v[10:11], v[16:17] op_sel_hi:[1,0]
	v_pk_mul_f32 v[10:11], v[8:9], v[16:17] op_sel_hi:[1,0]
	v_cvt_pk_bf16_f32 v8, v12, v13
	v_mad_i64_i32 v[12:13], s[20:21], v17, s64, v[120:121]
	v_pk_mul_f32 v[14:15], v[14:15], v[16:17] op_sel_hi:[1,0]
	v_lshl_add_u64 v[12:13], v[12:13], 0, v[122:123]
	v_cvt_pk_bf16_f32 v9, v14, v15
	v_cvt_pk_bf16_f32 v10, v10, v11
	v_cvt_pk_bf16_f32 v11, v18, v19
	global_store_dwordx4 v[12:13], v[8:11], off sc1
	s_mov_b64 s[20:21], -1
	s_andn2_b64 vcc, exec, s[8:9]
	v_pk_mul_f32 v[8:9], v[2:3], v[16:17] op_sel_hi:[1,0]
	v_pk_mul_f32 v[2:3], v[0:1], v[16:17] op_sel_hi:[1,0]
	v_pk_mul_f32 v[6:7], v[6:7], v[16:17] op_sel_hi:[1,0]
	v_pk_mul_f32 v[4:5], v[4:5], v[16:17] op_sel_hi:[1,0]
	v_cvt_pk_bf16_f32 v1, v6, v7
	v_cvt_pk_bf16_f32 v2, v2, v3
	v_cvt_pk_bf16_f32 v3, v8, v9
	s_nop 0
	v_cvt_pk_bf16_f32 v0, v4, v5
	global_store_dwordx4 v[12:13], v[0:3], off offset:256 sc1
	s_cbranch_vccnz .LBB0_535
	s_andn2_b64 vcc, exec, s[18:19]
	s_cbranch_vccnz .LBB0_534
	s_barrier
	s_branch .LBB0_534

; DI unsigned cvt_pk(float lo, float hi) { unsigned r; asm("v_cvt_pk_bf16_f32 %0, %1, %2" : "=v"(r) : "v"(lo), "v"(hi)); return r; }
; DI float siluf_(float x) { return x * sigmoidf_(x); }
;     __device__ __forceinline__ void operator()(const f32x4 (&acc)[2][2][4][2], const Unit& u, int wr, int wc, int fr, int fq) const {
;         const int row0 = u.pm * BM + wr * 64 + fr, col0 = u.pn * 128 + wc * 32 + 8 * fq;
; #pragma unroll
;         for (int ai = 0; ai < 2; ++ai)
; #pragma unroll
;             for (int m = 0; m < 4; ++m) {
;                 const int row = row0 + ai * HALF + m * 16;
;                 const float rs = rsqrtf(ss[row] * (1.f / DM) + EPS);
;                 float h[8];
; #pragma unroll
;                 for (int n = 0; n < 2; ++n)
; #pragma unroll
;                     for (int j = 0; j < 4; ++j) { const float gg = acc[ai][0][m][n][j] * rs, uu = acc[ai][1][m][n][j] * rs; h[4 * n + j] = siluf_(gg) * uu; }
;                 u32x4 w; w.x = cvt_pk(h[0], h[1]); w.y = cvt_pk(h[2], h[3]); w.z = cvt_pk(h[4], h[5]); w.w = cvt_pk(h[6], h[7]);
;                 *(u32x4*)(H + (size_t)row * DFF + col0) = w;
.LBB0_1298:
	v_lshl_add_u32 v138, s41, 8, v155
	v_ashrrev_i32_e32 v139, 31, v138
	v_lshl_add_u64 v[140:141], v[138:139], 2, s[10:11]
	global_load_dword v139, v[140:141], off
	global_load_dword v162, v[140:141], off offset:64
	global_load_dword v163, v[140:141], off offset:128
	global_load_dword v164, v[140:141], off offset:192
	global_load_dword v165, v[140:141], off offset:512
	global_load_dword v166, v[140:141], off offset:576
	global_load_dword v167, v[140:141], off offset:640
	global_load_dword v168, v[140:141], off offset:704
	s_mov_b32 s15, 0x800000
	v_lshl_or_b32 v142, s40, 7, v157
	v_ashrrev_i32_e32 v143, 31, v142
	v_mov_b64_e32 v[186:187], s[4:5]
	v_lshlrev_b64 v[188:189], 1, v[142:143]
	s_waitcnt vmcnt(0)
	v_fmamk_f32 v180, v139, 0x3a800000, v217
	v_cmp_gt_f32_e32 vcc, s15, v180
	v_mul_f32_e32 v181, 0x4b800000, v180
	s_nop 0
	v_cndmask_b32_e32 v180, v180, v181, vcc
	v_rsq_f32_e32 v180, v180
	v_add_u32_e32 v182, 0, v138
	v_mul_f32_e32 v181, 0x45800000, v180
	v_cndmask_b32_e32 v180, v180, v181, vcc
	v_mul_f32_e32 v124, v124, v180
	v_mul_f32_e32 v120, v120, v180
	v_mul_f32_e32 v125, v125, v180
	v_mul_f32_e32 v121, v121, v180
	v_mul_f32_e32 v126, v126, v180
	v_mul_f32_e32 v122, v122, v180
	v_mul_f32_e32 v127, v127, v180
	v_mul_f32_e32 v123, v123, v180
	v_mul_f32_e32 v116, v116, v180
	v_mul_f32_e32 v112, v112, v180
	v_mul_f32_e32 v117, v117, v180
	v_mul_f32_e32 v113, v113, v180
	v_mul_f32_e32 v118, v118, v180
	v_mul_f32_e32 v114, v114, v180
	v_mul_f32_e32 v119, v119, v180
	v_mul_f32_e32 v115, v115, v180
	v_mul_f32_e32 v172, 0xbfb8aa3b, v124
	v_mul_f32_e32 v173, 0xbfb8aa3b, v125
	v_mul_f32_e32 v174, 0xbfb8aa3b, v126
	v_mul_f32_e32 v175, 0xbfb8aa3b, v127
	v_mul_f32_e32 v176, 0xbfb8aa3b, v116
	v_mul_f32_e32 v177, 0xbfb8aa3b, v117
	v_mul_f32_e32 v178, 0xbfb8aa3b, v118
	v_mul_f32_e32 v179, 0xbfb8aa3b, v119
	v_exp_f32_e32 v172, v172
	v_exp_f32_e32 v173, v173
	v_exp_f32_e32 v174, v174
	v_exp_f32_e32 v175, v175
	v_exp_f32_e32 v176, v176
	v_exp_f32_e32 v177, v177
	v_exp_f32_e32 v178, v178
	v_exp_f32_e32 v179, v179
	v_add_f32_e32 v172, 1.0, v172
	v_add_f32_e32 v173, 1.0, v173
	v_add_f32_e32 v174, 1.0, v174
	v_add_f32_e32 v175, 1.0, v175
	v_add_f32_e32 v176, 1.0, v176
	v_add_f32_e32 v177, 1.0, v177
	v_add_f32_e32 v178, 1.0, v178
	v_add_f32_e32 v179, 1.0, v179
	v_rcp_f32_e32 v172, v172
	v_rcp_f32_e32 v173, v173
	v_rcp_f32_e32 v174, v174
	v_rcp_f32_e32 v175, v175
	v_rcp_f32_e32 v176, v176
	v_rcp_f32_e32 v177, v177
	v_rcp_f32_e32 v178, v178
	v_rcp_f32_e32 v179, v179
	v_mul_f32_e32 v124, v124, v172
	v_mul_f32_e32 v125, v125, v173
	v_mul_f32_e32 v126, v126, v174
	v_mul_f32_e32 v127, v127, v175
	v_mul_f32_e32 v116, v116, v176
	v_mul_f32_e32 v117, v117, v177
	v_mul_f32_e32 v118, v118, v178
	v_mul_f32_e32 v119, v119, v179
	v_mul_f32_e32 v124, v120, v124
	v_mul_f32_e32 v125, v121, v125
	v_mul_f32_e32 v126, v122, v126
	v_mul_f32_e32 v127, v123, v127
	v_mul_f32_e32 v116, v112, v116
	v_mul_f32_e32 v117, v113, v117
	v_mul_f32_e32 v118, v114, v118
	v_mul_f32_e32 v119, v115, v119
	v_mad_i64_i32 v[184:185], s[22:23], v182, s64, v[186:187]
	v_cvt_pk_bf16_f32 v172, v124, v125
	v_cvt_pk_bf16_f32 v173, v126, v127
	v_cvt_pk_bf16_f32 v174, v116, v117
	v_cvt_pk_bf16_f32 v175, v118, v119
	v_lshl_add_u64 v[184:185], v[184:185], 0, v[188:189]
	global_store_dwordx4 v[184:185], v[172:175], off sc1
	v_fmamk_f32 v180, v162, 0x3a800000, v217
	v_cmp_gt_f32_e32 vcc, s15, v180
	v_mul_f32_e32 v181, 0x4b800000, v180
	s_nop 0
	v_cndmask_b32_e32 v180, v180, v181, vcc
	v_rsq_f32_e32 v180, v180
	v_add_u32_e32 v182, 16, v138
	v_mul_f32_e32 v181, 0x45800000, v180
	v_cndmask_b32_e32 v180, v180, v181, vcc
	v_mul_f32_e32 v108, v108, v180
	v_mul_f32_e32 v104, v104, v180
	v_mul_f32_e32 v109, v109, v180
	v_mul_f32_e32 v105, v105, v180
	v_mul_f32_e32 v110, v110, v180
	v_mul_f32_e32 v106, v106, v180
	v_mul_f32_e32 v111, v111, v180
	v_mul_f32_e32 v107, v107, v180
	v_mul_f32_e32 v100, v100, v180
	v_mul_f32_e32 v96, v96, v180
	v_mul_f32_e32 v101, v101, v180
	v_mul_f32_e32 v97, v97, v180
	v_mul_f32_e32 v102, v102, v180
	v_mul_f32_e32 v98, v98, v180
	v_mul_f32_e32 v103, v103, v180
	v_mul_f32_e32 v99, v99, v180
	v_mul_f32_e32 v172, 0xbfb8aa3b, v108
	v_mul_f32_e32 v173, 0xbfb8aa3b, v109
	v_mul_f32_e32 v174, 0xbfb8aa3b, v110
	v_mul_f32_e32 v175, 0xbfb8aa3b, v111
	v_mul_f32_e32 v176, 0xbfb8aa3b, v100
	v_mul_f32_e32 v177, 0xbfb8aa3b, v101
	v_mul_f32_e32 v178, 0xbfb8aa3b, v102
	v_mul_f32_e32 v179, 0xbfb8aa3b, v103
	v_exp_f32_e32 v172, v172
	v_exp_f32_e32 v173, v173
	v_exp_f32_e32 v174, v174
	v_exp_f32_e32 v175, v175
	v_exp_f32_e32 v176, v176
	v_exp_f32_e32 v177, v177
	v_exp_f32_e32 v178, v178
	v_exp_f32_e32 v179, v179
	v_add_f32_e32 v172, 1.0, v172
	v_add_f32_e32 v173, 1.0, v173
	v_add_f32_e32 v174, 1.0, v174
	v_add_f32_e32 v175, 1.0, v175
	v_add_f32_e32 v176, 1.0, v176
	v_add_f32_e32 v177, 1.0, v177
	v_add_f32_e32 v178, 1.0, v178
	v_add_f32_e32 v179, 1.0, v179
	v_rcp_f32_e32 v172, v172
	v_rcp_f32_e32 v173, v173
	v_rcp_f32_e32 v174, v174
	v_rcp_f32_e32 v175, v175
	v_rcp_f32_e32 v176, v176
	v_rcp_f32_e32 v177, v177
	v_rcp_f32_e32 v178, v178
	v_rcp_f32_e32 v179, v179
	v_mul_f32_e32 v108, v108, v172
	v_mul_f32_e32 v109, v109, v173
	v_mul_f32_e32 v110, v110, v174
	v_mul_f32_e32 v111, v111, v175
	v_mul_f32_e32 v100, v100, v176
	v_mul_f32_e32 v101, v101, v177
	v_mul_f32_e32 v102, v102, v178
	v_mul_f32_e32 v103, v103, v179
	v_mul_f32_e32 v108, v104, v108
	v_mul_f32_e32 v109, v105, v109
	v_mul_f32_e32 v110, v106, v110
	v_mul_f32_e32 v111, v107, v111
	v_mul_f32_e32 v100, v96, v100
	v_mul_f32_e32 v101, v97, v101
	v_mul_f32_e32 v102, v98, v102
	v_mul_f32_e32 v103, v99, v103
	v_mad_i64_i32 v[184:185], s[22:23], v182, s64, v[186:187]
; DI unsigned cvt_pk(float lo, float hi) { unsigned r; asm("v_cvt_pk_bf16_f32 %0, %1, %2" : "=v"(r) : "v"(lo), "v"(hi)); return r; }
; DI float siluf_(float x) { return x * sigmoidf_(x); }
;     __device__ __forceinline__ void operator()(const f32x4 (&acc)[2][2][4][2], const Unit& u, int wr, int wc, int fr, int fq) const {
;         const int row0 = u.pm * BM + wr * 64 + fr, col0 = u.pn * 128 + wc * 32 + 8 * fq;
; #pragma unroll
;         for (int ai = 0; ai < 2; ++ai)
; #pragma unroll
;             for (int m = 0; m < 4; ++m) {
;                 const int row = row0 + ai * HALF + m * 16;
;                 const float rs = rsqrtf(ss[row] * (1.f / DM) + EPS);
;                 float h[8];
; #pragma unroll
;                 for (int n = 0; n < 2; ++n)
; #pragma unroll
;                     for (int j = 0; j < 4; ++j) { const float gg = acc[ai][0][m][n][j] * rs, uu = acc[ai][1][m][n][j] * rs; h[4 * n + j] = siluf_(gg) * uu; }
;                 u32x4 w; w.x = cvt_pk(h[0], h[1]); w.y = cvt_pk(h[2], h[3]); w.z = cvt_pk(h[4], h[5]); w.w = cvt_pk(h[6], h[7]);
;                 *(u32x4*)(H + (size_t)row * DFF + col0) = w;
	v_cvt_pk_bf16_f32 v172, v108, v109
	v_cvt_pk_bf16_f32 v173, v110, v111
	v_cvt_pk_bf16_f32 v174, v100, v101
	v_cvt_pk_bf16_f32 v175, v102, v103
	v_lshl_add_u64 v[184:185], v[184:185], 0, v[188:189]
	global_store_dwordx4 v[184:185], v[172:175], off sc1
	v_fmamk_f32 v180, v163, 0x3a800000, v217
	v_cmp_gt_f32_e32 vcc, s15, v180
	v_mul_f32_e32 v181, 0x4b800000, v180
	s_nop 0
	v_cndmask_b32_e32 v180, v180, v181, vcc
	v_rsq_f32_e32 v180, v180
	v_add_u32_e32 v182, 32, v138
	v_mul_f32_e32 v181, 0x45800000, v180
	v_cndmask_b32_e32 v180, v180, v181, vcc
	v_mul_f32_e32 v92, v92, v180
	v_mul_f32_e32 v88, v88, v180
	v_mul_f32_e32 v93, v93, v180
	v_mul_f32_e32 v89, v89, v180
	v_mul_f32_e32 v94, v94, v180
	v_mul_f32_e32 v90, v90, v180
	v_mul_f32_e32 v95, v95, v180
	v_mul_f32_e32 v91, v91, v180
	v_mul_f32_e32 v84, v84, v180
	v_mul_f32_e32 v80, v80, v180
	v_mul_f32_e32 v85, v85, v180
	v_mul_f32_e32 v81, v81, v180
	v_mul_f32_e32 v86, v86, v180
	v_mul_f32_e32 v82, v82, v180
	v_mul_f32_e32 v87, v87, v180
	v_mul_f32_e32 v83, v83, v180
	v_mul_f32_e32 v172, 0xbfb8aa3b, v92
	v_mul_f32_e32 v173, 0xbfb8aa3b, v93
	v_mul_f32_e32 v174, 0xbfb8aa3b, v94
	v_mul_f32_e32 v175, 0xbfb8aa3b, v95
	v_mul_f32_e32 v176, 0xbfb8aa3b, v84
	v_mul_f32_e32 v177, 0xbfb8aa3b, v85
	v_mul_f32_e32 v178, 0xbfb8aa3b, v86
	v_mul_f32_e32 v179, 0xbfb8aa3b, v87
	v_exp_f32_e32 v172, v172
	v_exp_f32_e32 v173, v173
	v_exp_f32_e32 v174, v174
	v_exp_f32_e32 v175, v175
	v_exp_f32_e32 v176, v176
	v_exp_f32_e32 v177, v177
	v_exp_f32_e32 v178, v178
	v_exp_f32_e32 v179, v179
	v_add_f32_e32 v172, 1.0, v172
	v_add_f32_e32 v173, 1.0, v173
	v_add_f32_e32 v174, 1.0, v174
	v_add_f32_e32 v175, 1.0, v175
	v_add_f32_e32 v176, 1.0, v176
	v_add_f32_e32 v177, 1.0, v177
	v_add_f32_e32 v178, 1.0, v178
	v_add_f32_e32 v179, 1.0, v179
	v_rcp_f32_e32 v172, v172
	v_rcp_f32_e32 v173, v173
	v_rcp_f32_e32 v174, v174
	v_rcp_f32_e32 v175, v175
	v_rcp_f32_e32 v176, v176
	v_rcp_f32_e32 v177, v177
	v_rcp_f32_e32 v178, v178
	v_rcp_f32_e32 v179, v179
	v_mul_f32_e32 v92, v92, v172
	v_mul_f32_e32 v93, v93, v173
	v_mul_f32_e32 v94, v94, v174
	v_mul_f32_e32 v95, v95, v175
	v_mul_f32_e32 v84, v84, v176
	v_mul_f32_e32 v85, v85, v177
	v_mul_f32_e32 v86, v86, v178
	v_mul_f32_e32 v87, v87, v179
	v_mul_f32_e32 v92, v88, v92
	v_mul_f32_e32 v93, v89, v93
	v_mul_f32_e32 v94, v90, v94
	v_mul_f32_e32 v95, v91, v95
	v_mul_f32_e32 v84, v80, v84
	v_mul_f32_e32 v85, v81, v85
	v_mul_f32_e32 v86, v82, v86
	v_mul_f32_e32 v87, v83, v87
	v_mad_i64_i32 v[184:185], s[22:23], v182, s64, v[186:187]
	v_cvt_pk_bf16_f32 v172, v92, v93
	v_cvt_pk_bf16_f32 v173, v94, v95
	v_cvt_pk_bf16_f32 v174, v84, v85
	v_cvt_pk_bf16_f32 v175, v86, v87
	v_lshl_add_u64 v[184:185], v[184:185], 0, v[188:189]
	global_store_dwordx4 v[184:185], v[172:175], off sc1
	v_fmamk_f32 v180, v164, 0x3a800000, v217
	v_cmp_gt_f32_e32 vcc, s15, v180
	v_mul_f32_e32 v181, 0x4b800000, v180
	s_nop 0
	v_cndmask_b32_e32 v180, v180, v181, vcc
	v_rsq_f32_e32 v180, v180
	v_add_u32_e32 v182, 48, v138
	v_mul_f32_e32 v181, 0x45800000, v180
	v_cndmask_b32_e32 v180, v180, v181, vcc
	v_mul_f32_e32 v76, v76, v180
	v_mul_f32_e32 v72, v72, v180
	v_mul_f32_e32 v77, v77, v180
	v_mul_f32_e32 v73, v73, v180
	v_mul_f32_e32 v78, v78, v180
	v_mul_f32_e32 v74, v74, v180
	v_mul_f32_e32 v79, v79, v180
	v_mul_f32_e32 v75, v75, v180
	v_mul_f32_e32 v68, v68, v180
	v_mul_f32_e32 v64, v64, v180
	v_mul_f32_e32 v69, v69, v180
	v_mul_f32_e32 v65, v65, v180
	v_mul_f32_e32 v70, v70, v180
	v_mul_f32_e32 v66, v66, v180
	v_mul_f32_e32 v71, v71, v180
	v_mul_f32_e32 v67, v67, v180
	v_mul_f32_e32 v172, 0xbfb8aa3b, v76
	v_mul_f32_e32 v173, 0xbfb8aa3b, v77
	v_mul_f32_e32 v174, 0xbfb8aa3b, v78
	v_mul_f32_e32 v175, 0xbfb8aa3b, v79
	v_mul_f32_e32 v176, 0xbfb8aa3b, v68
	v_mul_f32_e32 v177, 0xbfb8aa3b, v69
	v_mul_f32_e32 v178, 0xbfb8aa3b, v70
	v_mul_f32_e32 v179, 0xbfb8aa3b, v71
	v_exp_f32_e32 v172, v172
	v_exp_f32_e32 v173, v173
	v_exp_f32_e32 v174, v174
	v_exp_f32_e32 v175, v175
	v_exp_f32_e32 v176, v176
	v_exp_f32_e32 v177, v177
	v_exp_f32_e32 v178, v178
	v_exp_f32_e32 v179, v179
	v_add_f32_e32 v172, 1.0, v172
	v_add_f32_e32 v173, 1.0, v173
	v_add_f32_e32 v174, 1.0, v174
	v_add_f32_e32 v175, 1.0, v175
	v_add_f32_e32 v176, 1.0, v176
	v_add_f32_e32 v177, 1.0, v177
	v_add_f32_e32 v178, 1.0, v178
	v_add_f32_e32 v179, 1.0, v179
	v_rcp_f32_e32 v172, v172
	v_rcp_f32_e32 v173, v173
	v_rcp_f32_e32 v174, v174
	v_rcp_f32_e32 v175, v175
	v_rcp_f32_e32 v176, v176
	v_rcp_f32_e32 v177, v177
	v_rcp_f32_e32 v178, v178
	v_rcp_f32_e32 v179, v179
	v_mul_f32_e32 v76, v76, v172
	v_mul_f32_e32 v77, v77, v173
	v_mul_f32_e32 v78, v78, v174
	v_mul_f32_e32 v79, v79, v175
	v_mul_f32_e32 v68, v68, v176
	v_mul_f32_e32 v69, v69, v177
	v_mul_f32_e32 v70, v70, v178
	v_mul_f32_e32 v71, v71, v179
	v_mul_f32_e32 v76, v72, v76
	v_mul_f32_e32 v77, v73, v77
	v_mul_f32_e32 v78, v74, v78
	v_mul_f32_e32 v79, v75, v79
	v_mul_f32_e32 v68, v64, v68
	v_mul_f32_e32 v69, v65, v69
	v_mul_f32_e32 v70, v66, v70
	v_mul_f32_e32 v71, v67, v71
	v_mad_i64_i32 v[184:185], s[22:23], v182, s64, v[186:187]
	v_cvt_pk_bf16_f32 v172, v76, v77
	v_cvt_pk_bf16_f32 v173, v78, v79
	v_cvt_pk_bf16_f32 v174, v68, v69
	v_cvt_pk_bf16_f32 v175, v70, v71
	v_lshl_add_u64 v[184:185], v[184:185], 0, v[188:189]
	global_store_dwordx4 v[184:185], v[172:175], off sc1
	v_fmamk_f32 v180, v165, 0x3a800000, v217
	v_cmp_gt_f32_e32 vcc, s15, v180
	v_mul_f32_e32 v181, 0x4b800000, v180
	s_nop 0
	v_cndmask_b32_e32 v180, v180, v181, vcc
	v_rsq_f32_e32 v180, v180
	v_add_u32_e32 v182, 128, v138
	v_mul_f32_e32 v181, 0x45800000, v180
	v_cndmask_b32_e32 v180, v180, v181, vcc
	v_mul_f32_e32 v60, v60, v180
	v_mul_f32_e32 v56, v56, v180
; DI unsigned cvt_pk(float lo, float hi) { unsigned r; asm("v_cvt_pk_bf16_f32 %0, %1, %2" : "=v"(r) : "v"(lo), "v"(hi)); return r; }
; DI float siluf_(float x) { return x * sigmoidf_(x); }
;     __device__ __forceinline__ void operator()(const f32x4 (&acc)[2][2][4][2], const Unit& u, int wr, int wc, int fr, int fq) const {
;         const int row0 = u.pm * BM + wr * 64 + fr, col0 = u.pn * 128 + wc * 32 + 8 * fq;
; #pragma unroll
;         for (int ai = 0; ai < 2; ++ai)
; #pragma unroll
;             for (int m = 0; m < 4; ++m) {
;                 const int row = row0 + ai * HALF + m * 16;
;                 const float rs = rsqrtf(ss[row] * (1.f / DM) + EPS);
;                 float h[8];
; #pragma unroll
;                 for (int n = 0; n < 2; ++n)
; #pragma unroll
;                     for (int j = 0; j < 4; ++j) { const float gg = acc[ai][0][m][n][j] * rs, uu = acc[ai][1][m][n][j] * rs; h[4 * n + j] = siluf_(gg) * uu; }
;                 u32x4 w; w.x = cvt_pk(h[0], h[1]); w.y = cvt_pk(h[2], h[3]); w.z = cvt_pk(h[4], h[5]); w.w = cvt_pk(h[6], h[7]);
;                 *(u32x4*)(H + (size_t)row * DFF + col0) = w;
	v_mul_f32_e32 v61, v61, v180
	v_mul_f32_e32 v57, v57, v180
	v_mul_f32_e32 v62, v62, v180
	v_mul_f32_e32 v58, v58, v180
	v_mul_f32_e32 v63, v63, v180
	v_mul_f32_e32 v59, v59, v180
	v_mul_f32_e32 v52, v52, v180
	v_mul_f32_e32 v48, v48, v180
	v_mul_f32_e32 v53, v53, v180
	v_mul_f32_e32 v49, v49, v180
	v_mul_f32_e32 v54, v54, v180
	v_mul_f32_e32 v50, v50, v180
	v_mul_f32_e32 v55, v55, v180
	v_mul_f32_e32 v51, v51, v180
	v_mul_f32_e32 v172, 0xbfb8aa3b, v60
	v_mul_f32_e32 v173, 0xbfb8aa3b, v61
	v_mul_f32_e32 v174, 0xbfb8aa3b, v62
	v_mul_f32_e32 v175, 0xbfb8aa3b, v63
	v_mul_f32_e32 v176, 0xbfb8aa3b, v52
	v_mul_f32_e32 v177, 0xbfb8aa3b, v53
	v_mul_f32_e32 v178, 0xbfb8aa3b, v54
	v_mul_f32_e32 v179, 0xbfb8aa3b, v55
	v_exp_f32_e32 v172, v172
	v_exp_f32_e32 v173, v173
	v_exp_f32_e32 v174, v174
	v_exp_f32_e32 v175, v175
	v_exp_f32_e32 v176, v176
	v_exp_f32_e32 v177, v177
	v_exp_f32_e32 v178, v178
	v_exp_f32_e32 v179, v179
	v_add_f32_e32 v172, 1.0, v172
	v_add_f32_e32 v173, 1.0, v173
	v_add_f32_e32 v174, 1.0, v174
	v_add_f32_e32 v175, 1.0, v175
	v_add_f32_e32 v176, 1.0, v176
	v_add_f32_e32 v177, 1.0, v177
	v_add_f32_e32 v178, 1.0, v178
	v_add_f32_e32 v179, 1.0, v179
	v_rcp_f32_e32 v172, v172
	v_rcp_f32_e32 v173, v173
	v_rcp_f32_e32 v174, v174
	v_rcp_f32_e32 v175, v175
	v_rcp_f32_e32 v176, v176
	v_rcp_f32_e32 v177, v177
	v_rcp_f32_e32 v178, v178
	v_rcp_f32_e32 v179, v179
	v_mul_f32_e32 v60, v60, v172
	v_mul_f32_e32 v61, v61, v173
	v_mul_f32_e32 v62, v62, v174
	v_mul_f32_e32 v63, v63, v175
	v_mul_f32_e32 v52, v52, v176
	v_mul_f32_e32 v53, v53, v177
	v_mul_f32_e32 v54, v54, v178
	v_mul_f32_e32 v55, v55, v179
	v_mul_f32_e32 v60, v56, v60
	v_mul_f32_e32 v61, v57, v61
	v_mul_f32_e32 v62, v58, v62
	v_mul_f32_e32 v63, v59, v63
	v_mul_f32_e32 v52, v48, v52
	v_mul_f32_e32 v53, v49, v53
	v_mul_f32_e32 v54, v50, v54
	v_mul_f32_e32 v55, v51, v55
	v_mad_i64_i32 v[184:185], s[22:23], v182, s64, v[186:187]
	v_cvt_pk_bf16_f32 v172, v60, v61
	v_cvt_pk_bf16_f32 v173, v62, v63
	v_cvt_pk_bf16_f32 v174, v52, v53
	v_cvt_pk_bf16_f32 v175, v54, v55
	v_lshl_add_u64 v[184:185], v[184:185], 0, v[188:189]
	global_store_dwordx4 v[184:185], v[172:175], off sc1
	v_fmamk_f32 v180, v166, 0x3a800000, v217
	v_cmp_gt_f32_e32 vcc, s15, v180
	v_mul_f32_e32 v181, 0x4b800000, v180
	s_nop 0
	v_cndmask_b32_e32 v180, v180, v181, vcc
	v_rsq_f32_e32 v180, v180
	v_add_u32_e32 v182, 144, v138
	v_mul_f32_e32 v181, 0x45800000, v180
	v_cndmask_b32_e32 v180, v180, v181, vcc
	v_mul_f32_e32 v44, v44, v180
	v_mul_f32_e32 v40, v40, v180
	v_mul_f32_e32 v45, v45, v180
	v_mul_f32_e32 v41, v41, v180
	v_mul_f32_e32 v46, v46, v180
	v_mul_f32_e32 v42, v42, v180
	v_mul_f32_e32 v47, v47, v180
	v_mul_f32_e32 v43, v43, v180
	v_mul_f32_e32 v36, v36, v180
	v_mul_f32_e32 v32, v32, v180
	v_mul_f32_e32 v37, v37, v180
	v_mul_f32_e32 v33, v33, v180
	v_mul_f32_e32 v38, v38, v180
	v_mul_f32_e32 v34, v34, v180
	v_mul_f32_e32 v39, v39, v180
	v_mul_f32_e32 v35, v35, v180
	v_mul_f32_e32 v172, 0xbfb8aa3b, v44
	v_mul_f32_e32 v173, 0xbfb8aa3b, v45
	v_mul_f32_e32 v174, 0xbfb8aa3b, v46
	v_mul_f32_e32 v175, 0xbfb8aa3b, v47
	v_mul_f32_e32 v176, 0xbfb8aa3b, v36
	v_mul_f32_e32 v177, 0xbfb8aa3b, v37
	v_mul_f32_e32 v178, 0xbfb8aa3b, v38
	v_mul_f32_e32 v179, 0xbfb8aa3b, v39
	v_exp_f32_e32 v172, v172
	v_exp_f32_e32 v173, v173
	v_exp_f32_e32 v174, v174
	v_exp_f32_e32 v175, v175
	v_exp_f32_e32 v176, v176
	v_exp_f32_e32 v177, v177
	v_exp_f32_e32 v178, v178
	v_exp_f32_e32 v179, v179
	v_add_f32_e32 v172, 1.0, v172
	v_add_f32_e32 v173, 1.0, v173
	v_add_f32_e32 v174, 1.0, v174
	v_add_f32_e32 v175, 1.0, v175
	v_add_f32_e32 v176, 1.0, v176
	v_add_f32_e32 v177, 1.0, v177
	v_add_f32_e32 v178, 1.0, v178
	v_add_f32_e32 v179, 1.0, v179
	v_rcp_f32_e32 v172, v172
	v_rcp_f32_e32 v173, v173
	v_rcp_f32_e32 v174, v174
	v_rcp_f32_e32 v175, v175
	v_rcp_f32_e32 v176, v176
	v_rcp_f32_e32 v177, v177
	v_rcp_f32_e32 v178, v178
	v_rcp_f32_e32 v179, v179
	v_mul_f32_e32 v44, v44, v172
	v_mul_f32_e32 v45, v45, v173
	v_mul_f32_e32 v46, v46, v174
	v_mul_f32_e32 v47, v47, v175
	v_mul_f32_e32 v36, v36, v176
	v_mul_f32_e32 v37, v37, v177
	v_mul_f32_e32 v38, v38, v178
	v_mul_f32_e32 v39, v39, v179
	v_mul_f32_e32 v44, v40, v44
	v_mul_f32_e32 v45, v41, v45
	v_mul_f32_e32 v46, v42, v46
	v_mul_f32_e32 v47, v43, v47
	v_mul_f32_e32 v36, v32, v36
	v_mul_f32_e32 v37, v33, v37
	v_mul_f32_e32 v38, v34, v38
	v_mul_f32_e32 v39, v35, v39
	v_mad_i64_i32 v[184:185], s[22:23], v182, s64, v[186:187]
	v_cvt_pk_bf16_f32 v172, v44, v45
	v_cvt_pk_bf16_f32 v173, v46, v47
	v_cvt_pk_bf16_f32 v174, v36, v37
	v_cvt_pk_bf16_f32 v175, v38, v39
	v_lshl_add_u64 v[184:185], v[184:185], 0, v[188:189]
	global_store_dwordx4 v[184:185], v[172:175], off sc1
	v_fmamk_f32 v180, v167, 0x3a800000, v217
	v_cmp_gt_f32_e32 vcc, s15, v180
	v_mul_f32_e32 v181, 0x4b800000, v180
	s_nop 0
	v_cndmask_b32_e32 v180, v180, v181, vcc
	v_rsq_f32_e32 v180, v180
	v_add_u32_e32 v182, 160, v138
	v_mul_f32_e32 v181, 0x45800000, v180
; DI unsigned cvt_pk(float lo, float hi) { unsigned r; asm("v_cvt_pk_bf16_f32 %0, %1, %2" : "=v"(r) : "v"(lo), "v"(hi)); return r; }
; DI float siluf_(float x) { return x * sigmoidf_(x); }
;     __device__ __forceinline__ void operator()(const f32x4 (&acc)[2][2][4][2], const Unit& u, int wr, int wc, int fr, int fq) const {
;         const int row0 = u.pm * BM + wr * 64 + fr, col0 = u.pn * 128 + wc * 32 + 8 * fq;
; #pragma unroll
;         for (int ai = 0; ai < 2; ++ai)
; #pragma unroll
;             for (int m = 0; m < 4; ++m) {
;                 const int row = row0 + ai * HALF + m * 16;
;                 const float rs = rsqrtf(ss[row] * (1.f / DM) + EPS);
;                 float h[8];
; #pragma unroll
;                 for (int n = 0; n < 2; ++n)
; #pragma unroll
;                     for (int j = 0; j < 4; ++j) { const float gg = acc[ai][0][m][n][j] * rs, uu = acc[ai][1][m][n][j] * rs; h[4 * n + j] = siluf_(gg) * uu; }
;                 u32x4 w; w.x = cvt_pk(h[0], h[1]); w.y = cvt_pk(h[2], h[3]); w.z = cvt_pk(h[4], h[5]); w.w = cvt_pk(h[6], h[7]);
;                 *(u32x4*)(H + (size_t)row * DFF + col0) = w;
	v_cndmask_b32_e32 v180, v180, v181, vcc
	v_mul_f32_e32 v28, v28, v180
	v_mul_f32_e32 v24, v24, v180
	v_mul_f32_e32 v29, v29, v180
	v_mul_f32_e32 v25, v25, v180
	v_mul_f32_e32 v30, v30, v180
	v_mul_f32_e32 v26, v26, v180
	v_mul_f32_e32 v31, v31, v180
	v_mul_f32_e32 v27, v27, v180
	v_mul_f32_e32 v20, v20, v180
	v_mul_f32_e32 v16, v16, v180
	v_mul_f32_e32 v21, v21, v180
	v_mul_f32_e32 v17, v17, v180
	v_mul_f32_e32 v22, v22, v180
	v_mul_f32_e32 v18, v18, v180
	v_mul_f32_e32 v23, v23, v180
	v_mul_f32_e32 v19, v19, v180
	v_mul_f32_e32 v172, 0xbfb8aa3b, v28
	v_mul_f32_e32 v173, 0xbfb8aa3b, v29
	v_mul_f32_e32 v174, 0xbfb8aa3b, v30
	v_mul_f32_e32 v175, 0xbfb8aa3b, v31
	v_mul_f32_e32 v176, 0xbfb8aa3b, v20
	v_mul_f32_e32 v177, 0xbfb8aa3b, v21
	v_mul_f32_e32 v178, 0xbfb8aa3b, v22
	v_mul_f32_e32 v179, 0xbfb8aa3b, v23
	v_exp_f32_e32 v172, v172
	v_exp_f32_e32 v173, v173
	v_exp_f32_e32 v174, v174
	v_exp_f32_e32 v175, v175
	v_exp_f32_e32 v176, v176
	v_exp_f32_e32 v177, v177
	v_exp_f32_e32 v178, v178
	v_exp_f32_e32 v179, v179
	v_add_f32_e32 v172, 1.0, v172
	v_add_f32_e32 v173, 1.0, v173
	v_add_f32_e32 v174, 1.0, v174
	v_add_f32_e32 v175, 1.0, v175
	v_add_f32_e32 v176, 1.0, v176
	v_add_f32_e32 v177, 1.0, v177
	v_add_f32_e32 v178, 1.0, v178
	v_add_f32_e32 v179, 1.0, v179
	v_rcp_f32_e32 v172, v172
	v_rcp_f32_e32 v173, v173
	v_rcp_f32_e32 v174, v174
	v_rcp_f32_e32 v175, v175
	v_rcp_f32_e32 v176, v176
	v_rcp_f32_e32 v177, v177
	v_rcp_f32_e32 v178, v178
	v_rcp_f32_e32 v179, v179
	v_mul_f32_e32 v28, v28, v172
	v_mul_f32_e32 v29, v29, v173
	v_mul_f32_e32 v30, v30, v174
	v_mul_f32_e32 v31, v31, v175
	v_mul_f32_e32 v20, v20, v176
	v_mul_f32_e32 v21, v21, v177
	v_mul_f32_e32 v22, v22, v178
	v_mul_f32_e32 v23, v23, v179
	v_mul_f32_e32 v28, v24, v28
	v_mul_f32_e32 v29, v25, v29
	v_mul_f32_e32 v30, v26, v30
	v_mul_f32_e32 v31, v27, v31
	v_mul_f32_e32 v20, v16, v20
	v_mul_f32_e32 v21, v17, v21
	v_mul_f32_e32 v22, v18, v22
	v_mul_f32_e32 v23, v19, v23
	v_mad_i64_i32 v[184:185], s[22:23], v182, s64, v[186:187]
	v_cvt_pk_bf16_f32 v172, v28, v29
	v_cvt_pk_bf16_f32 v173, v30, v31
	v_cvt_pk_bf16_f32 v174, v20, v21
	v_cvt_pk_bf16_f32 v175, v22, v23
	v_lshl_add_u64 v[184:185], v[184:185], 0, v[188:189]
	global_store_dwordx4 v[184:185], v[172:175], off sc1
	v_fmamk_f32 v180, v168, 0x3a800000, v217
	v_cmp_gt_f32_e32 vcc, s15, v180
	v_mul_f32_e32 v181, 0x4b800000, v180
	s_nop 0
	v_cndmask_b32_e32 v180, v180, v181, vcc
	v_rsq_f32_e32 v180, v180
	v_add_u32_e32 v182, 176, v138
	v_mul_f32_e32 v181, 0x45800000, v180
	v_cndmask_b32_e32 v180, v180, v181, vcc
	v_mul_f32_e32 v12, v12, v180
	v_mul_f32_e32 v8, v8, v180
	v_mul_f32_e32 v13, v13, v180
	v_mul_f32_e32 v9, v9, v180
	v_mul_f32_e32 v14, v14, v180
	v_mul_f32_e32 v10, v10, v180
	v_mul_f32_e32 v15, v15, v180
	v_mul_f32_e32 v11, v11, v180
	v_mul_f32_e32 v4, v4, v180
	v_mul_f32_e32 v0, v0, v180
	v_mul_f32_e32 v5, v5, v180
	v_mul_f32_e32 v1, v1, v180
	v_mul_f32_e32 v6, v6, v180
	v_mul_f32_e32 v2, v2, v180
	v_mul_f32_e32 v7, v7, v180
	v_mul_f32_e32 v3, v3, v180
	v_mul_f32_e32 v172, 0xbfb8aa3b, v12
	v_mul_f32_e32 v173, 0xbfb8aa3b, v13
	v_mul_f32_e32 v174, 0xbfb8aa3b, v14
	v_mul_f32_e32 v175, 0xbfb8aa3b, v15
	v_mul_f32_e32 v176, 0xbfb8aa3b, v4
	v_mul_f32_e32 v177, 0xbfb8aa3b, v5
	v_mul_f32_e32 v178, 0xbfb8aa3b, v6
	v_mul_f32_e32 v179, 0xbfb8aa3b, v7
	v_exp_f32_e32 v172, v172
	v_exp_f32_e32 v173, v173
	v_exp_f32_e32 v174, v174
	v_exp_f32_e32 v175, v175
	v_exp_f32_e32 v176, v176
	v_exp_f32_e32 v177, v177
	v_exp_f32_e32 v178, v178
	v_exp_f32_e32 v179, v179
	v_add_f32_e32 v172, 1.0, v172
	v_add_f32_e32 v173, 1.0, v173
	v_add_f32_e32 v174, 1.0, v174
	v_add_f32_e32 v175, 1.0, v175
	v_add_f32_e32 v176, 1.0, v176
	v_add_f32_e32 v177, 1.0, v177
	v_add_f32_e32 v178, 1.0, v178
	v_add_f32_e32 v179, 1.0, v179
	v_rcp_f32_e32 v172, v172
	v_rcp_f32_e32 v173, v173
	v_rcp_f32_e32 v174, v174
	v_rcp_f32_e32 v175, v175
	v_rcp_f32_e32 v176, v176
	v_rcp_f32_e32 v177, v177
	v_rcp_f32_e32 v178, v178
	v_rcp_f32_e32 v179, v179
	v_mul_f32_e32 v12, v12, v172
	v_mul_f32_e32 v13, v13, v173
	v_mul_f32_e32 v14, v14, v174
	v_mul_f32_e32 v15, v15, v175
	v_mul_f32_e32 v4, v4, v176
	v_mul_f32_e32 v5, v5, v177
	v_mul_f32_e32 v6, v6, v178
	v_mul_f32_e32 v7, v7, v179
	v_mul_f32_e32 v12, v8, v12
	v_mul_f32_e32 v13, v9, v13
	v_mul_f32_e32 v14, v10, v14
	v_mul_f32_e32 v15, v11, v15
	v_mul_f32_e32 v4, v0, v4
	v_mul_f32_e32 v5, v1, v5
	v_mul_f32_e32 v6, v2, v6
	v_mul_f32_e32 v7, v3, v7
	v_mad_i64_i32 v[184:185], s[22:23], v182, s64, v[186:187]
	v_cvt_pk_bf16_f32 v172, v12, v13
	v_cvt_pk_bf16_f32 v173, v14, v15
	v_cvt_pk_bf16_f32 v174, v4, v5
	v_cvt_pk_bf16_f32 v175, v6, v7
	v_lshl_add_u64 v[184:185], v[184:185], 0, v[188:189]
	global_store_dwordx4 v[184:185], v[172:175], off sc1
	s_mov_b64 s[22:23], -1
	s_andn2_b64 vcc, exec, s[6:7]
	s_cbranch_vccnz .LBB0_1287
	s_andn2_b64 vcc, exec, s[2:3]
	s_cbranch_vccnz .LBB0_1286
	s_barrier
	s_branch .LBB0_1286
